# P1 specialised waves: waves 0/1 run the f32-MFMA CV tiles while waves 2..7 run the hand-scheduled norm rows (192-wave mapping)
# baseline (speedup 1.0000x reference)
.LBB0_441:
	s_waitcnt lgkmcnt(0)
	s_cmp_lt_u32 s69, 2
	s_cbranch_scc1 .LBB0_443
	v_mbcnt_lo_u32_b32 v207, -1, 0
	v_mbcnt_hi_u32_b32 v207, -1, v207
	v_lshlrev_b32_e32 v208, 3, v207
	v_lshlrev_b32_e32 v207, 4, v207
	v_mov_b32_e32 v206, 0x358637bd
	s_mov_b32 s22, 0x3a800000
	v_readlane_b32 s5, v254, 14
	v_readlane_b32 s2, v254, 8
	v_readlane_b32 s3, v254, 9
	s_mul_i32 s5, s5, 6
	s_add_i32 s5, s5, s69
	s_add_i32 s5, s5, -2
	s_cmp_lt_u32 s5, 64
	s_cselect_b32 s23, 0xc0000, 0
	s_cselect_b32 s28, 0x60000, 0
	s_lshl_b32 s4, s78, 24
	s_add_u32 s0, s12, s4
	s_addc_u32 s1, s13, 0
	s_lshl_b32 s4, s5, 12
	s_add_u32 s0, s0, s4
	s_addc_u32 s1, s1, 0
	s_add_u32 s2, s2, 0x4000000
	s_addc_u32 s3, s3, 0
	s_lshl_b32 s4, s78, 23
	s_add_u32 s2, s2, s4
	s_addc_u32 s3, s3, 0
	s_lshl_b32 s4, s5, 11
	s_add_u32 s2, s2, s4
	s_addc_u32 s3, s3, 0
	s_mul_i32 s4, s78, 0x12000
	s_add_u32 s8, s64, s4
	s_addc_u32 s9, s65, 0
	global_load_dwordx4 v[178:181], v207, s[8:9]
	global_load_dwordx4 v[182:185], v207, s[8:9] offset:1024
	global_load_dwordx4 v[186:189], v207, s[8:9] offset:2048
	global_load_dwordx4 v[190:193], v207, s[8:9] offset:3072
	s_add_u32 s8, s8, 0x1000
	s_addc_u32 s9, s9, 0
	global_load_dwordx4 v[162:165], v207, s[8:9]
	global_load_dwordx4 v[166:169], v207, s[8:9] offset:1024
	global_load_dwordx4 v[170:173], v207, s[8:9] offset:2048
	global_load_dwordx4 v[174:177], v207, s[8:9] offset:3072
	s_add_u32 s8, s8, 0x8000
	s_addc_u32 s9, s9, 0
	global_load_dwordx4 v[238:241], v207, s[8:9]
	global_load_dwordx4 v[242:245], v207, s[8:9] offset:1024
	global_load_dwordx4 v[246:249], v207, s[8:9] offset:2048
	global_load_dwordx4 v[250:253], v207, s[8:9] offset:3072
	s_add_u32 s8, s8, 0x1000
	s_addc_u32 s9, s9, 0
	global_load_dwordx4 v[222:225], v207, s[8:9]
	global_load_dwordx4 v[226:229], v207, s[8:9] offset:1024
	global_load_dwordx4 v[230:233], v207, s[8:9] offset:2048
	global_load_dwordx4 v[234:237], v207, s[8:9] offset:3072
	global_load_dwordx4 v[98:101], v207, s[0:1]
	global_load_dwordx4 v[102:105], v207, s[0:1] offset:1024
	global_load_dwordx4 v[106:109], v207, s[0:1] offset:2048
	global_load_dwordx4 v[110:113], v207, s[0:1] offset:3072
	s_add_u32 s0, s0, 0xc0000
	s_addc_u32 s1, s1, 0
	global_load_dwordx4 v[114:117], v207, s[0:1]
	global_load_dwordx4 v[118:121], v207, s[0:1] offset:1024
	global_load_dwordx4 v[122:125], v207, s[0:1] offset:2048
	global_load_dwordx4 v[126:129], v207, s[0:1] offset:3072
	s_add_u32 s0, s0, 0xc0000
	s_addc_u32 s1, s1, 0
	global_load_dwordx4 v[130:133], v207, s[0:1]
	global_load_dwordx4 v[134:137], v207, s[0:1] offset:1024
	global_load_dwordx4 v[138:141], v207, s[0:1] offset:2048
	global_load_dwordx4 v[142:145], v207, s[0:1] offset:3072
	s_add_u32 s0, s0, 0xc0000
	s_addc_u32 s1, s1, 0
	global_load_dwordx4 v[146:149], v207, s[0:1]
	global_load_dwordx4 v[150:153], v207, s[0:1] offset:1024
	global_load_dwordx4 v[154:157], v207, s[0:1] offset:2048
	global_load_dwordx4 v[158:161], v207, s[0:1] offset:3072
	s_add_u32 s0, s0, 0xc0000
	s_addc_u32 s1, s1, 0
	s_waitcnt vmcnt(8)
	v_mul_f32_e32 v194, v98, v98
	v_mul_f32_e32 v195, v102, v102
	v_mul_f32_e32 v196, v106, v106
	v_mul_f32_e32 v197, v110, v110
	v_mul_f32_e32 v198, v114, v114
	v_mul_f32_e32 v199, v118, v118
	v_mul_f32_e32 v200, v122, v122
	v_mul_f32_e32 v201, v126, v126
	v_fmac_f32_e32 v194, v99, v99
	v_fmac_f32_e32 v195, v103, v103
	v_fmac_f32_e32 v196, v107, v107
	v_fmac_f32_e32 v197, v111, v111
	v_fmac_f32_e32 v198, v115, v115
	v_fmac_f32_e32 v199, v119, v119
	v_fmac_f32_e32 v200, v123, v123
	v_fmac_f32_e32 v201, v127, v127
	v_fmac_f32_e32 v194, v100, v100
	v_fmac_f32_e32 v195, v104, v104
	v_fmac_f32_e32 v196, v108, v108
	v_fmac_f32_e32 v197, v112, v112
	v_fmac_f32_e32 v198, v116, v116
	v_fmac_f32_e32 v199, v120, v120
	v_fmac_f32_e32 v200, v124, v124
	v_fmac_f32_e32 v201, v128, v128
	v_fmac_f32_e32 v194, v101, v101
	v_fmac_f32_e32 v195, v105, v105
	v_fmac_f32_e32 v196, v109, v109
	v_fmac_f32_e32 v197, v113, v113
	v_fmac_f32_e32 v198, v117, v117
	v_fmac_f32_e32 v199, v121, v121
	v_fmac_f32_e32 v200, v125, v125
	v_fmac_f32_e32 v201, v129, v129
	v_add_f32_e32 v194, v194, v195
	v_add_f32_e32 v196, v196, v197
	v_add_f32_e32 v198, v198, v199
	v_add_f32_e32 v200, v200, v201
	v_add_f32_e32 v202, v194, v196
	v_add_f32_e32 v203, v198, v200
	s_nop 0
	v_add_f32_dpp v202, v202, v202 quad_perm:[1,0,3,2] row_mask:0xf bank_mask:0xf
	v_add_f32_dpp v203, v203, v203 quad_perm:[1,0,3,2] row_mask:0xf bank_mask:0xf
	s_nop 0
	v_add_f32_dpp v202, v202, v202 quad_perm:[2,3,0,1] row_mask:0xf bank_mask:0xf
	v_add_f32_dpp v203, v203, v203 quad_perm:[2,3,0,1] row_mask:0xf bank_mask:0xf
	s_nop 0
	v_add_f32_dpp v202, v202, v202 row_half_mirror row_mask:0xf bank_mask:0xf
	v_add_f32_dpp v203, v203, v203 row_half_mirror row_mask:0xf bank_mask:0xf
	s_nop 0
	v_add_f32_dpp v202, v202, v202 row_mirror row_mask:0xf bank_mask:0xf
	v_add_f32_dpp v203, v203, v203 row_mirror row_mask:0xf bank_mask:0xf
	s_nop 0
	v_add_f32_dpp v202, v202, v202 row_bcast:15 row_mask:0xa bank_mask:0xf
	v_add_f32_dpp v203, v203, v203 row_bcast:15 row_mask:0xa bank_mask:0xf
	s_nop 0
	v_add_f32_dpp v202, v202, v202 row_bcast:31 row_mask:0xc bank_mask:0xf
	v_add_f32_dpp v203, v203, v203 row_bcast:31 row_mask:0xc bank_mask:0xf
	s_nop 0
	v_fma_f32 v202, v202, s22, v206
	v_fma_f32 v203, v203, s22, v206
	v_rsq_f32_e32 v202, v202
	v_rsq_f32_e32 v203, v203
	s_nop 0
	v_readlane_b32 s10, v202, 63
	v_readlane_b32 s11, v203, 63
	s_nop 1
	v_mul_f32_e32 v204, s10, v98
	v_fma_f32 v98, v204, v162, v178
	v_mul_f32_e32 v205, s10, v99
	v_fma_f32 v99, v205, v163, v179
	v_mul_f32_e32 v204, s10, v100
	v_fma_f32 v100, v204, v164, v180
	v_mul_f32_e32 v205, s10, v101
	v_fma_f32 v101, v205, v165, v181
	v_mul_f32_e32 v204, s10, v102
	v_fma_f32 v102, v204, v166, v182
	v_mul_f32_e32 v205, s10, v103
	v_fma_f32 v103, v205, v167, v183
	v_mul_f32_e32 v204, s10, v104
	v_fma_f32 v104, v204, v168, v184
	v_mul_f32_e32 v205, s10, v105
	v_fma_f32 v105, v205, v169, v185
	v_mul_f32_e32 v204, s10, v106
	v_fma_f32 v106, v204, v170, v186
	v_mul_f32_e32 v205, s10, v107
	v_fma_f32 v107, v205, v171, v187
	v_mul_f32_e32 v204, s10, v108
	v_fma_f32 v108, v204, v172, v188
	v_mul_f32_e32 v205, s10, v109
	v_fma_f32 v109, v205, v173, v189
	v_mul_f32_e32 v204, s10, v110
	v_fma_f32 v110, v204, v174, v190
	v_mul_f32_e32 v205, s10, v111
	v_fma_f32 v111, v205, v175, v191
	v_mul_f32_e32 v204, s10, v112
	v_fma_f32 v112, v204, v176, v192
	v_mul_f32_e32 v205, s10, v113
	v_fma_f32 v113, v205, v177, v193
	v_cvt_pk_bf16_f32 v214, v98, v99
	v_cvt_pk_bf16_f32 v215, v100, v101
	v_cvt_pk_bf16_f32 v216, v102, v103
	v_cvt_pk_bf16_f32 v217, v104, v105
	v_cvt_pk_bf16_f32 v218, v106, v107
	v_cvt_pk_bf16_f32 v219, v108, v109
	v_cvt_pk_bf16_f32 v220, v110, v111
	v_cvt_pk_bf16_f32 v221, v112, v113
	global_store_dwordx2 v208, v[214:215], s[2:3]
	global_store_dwordx2 v208, v[216:217], s[2:3] offset:512
	global_store_dwordx2 v208, v[218:219], s[2:3] offset:1024
	global_store_dwordx2 v208, v[220:221], s[2:3] offset:1536
	s_add_u32 s2, s2, 0x60000
	s_addc_u32 s3, s3, 0
	v_mul_f32_e32 v204, s11, v114
	v_fma_f32 v114, v204, v162, v178
	v_mul_f32_e32 v205, s11, v115
	v_fma_f32 v115, v205, v163, v179
	v_mul_f32_e32 v204, s11, v116
	v_fma_f32 v116, v204, v164, v180
	v_mul_f32_e32 v205, s11, v117
	v_fma_f32 v117, v205, v165, v181
	v_mul_f32_e32 v204, s11, v118
	v_fma_f32 v118, v204, v166, v182
	v_mul_f32_e32 v205, s11, v119
	v_fma_f32 v119, v205, v167, v183
	v_mul_f32_e32 v204, s11, v120
	v_fma_f32 v120, v204, v168, v184
	v_mul_f32_e32 v205, s11, v121
	v_fma_f32 v121, v205, v169, v185
	v_mul_f32_e32 v204, s11, v122
	v_fma_f32 v122, v204, v170, v186
	v_mul_f32_e32 v205, s11, v123
	v_fma_f32 v123, v205, v171, v187
	v_mul_f32_e32 v204, s11, v124
	v_fma_f32 v124, v204, v172, v188
	v_mul_f32_e32 v205, s11, v125
	v_fma_f32 v125, v205, v173, v189
	v_mul_f32_e32 v204, s11, v126
	v_fma_f32 v126, v204, v174, v190
	v_mul_f32_e32 v205, s11, v127
	v_fma_f32 v127, v205, v175, v191
	v_mul_f32_e32 v204, s11, v128
	v_fma_f32 v128, v204, v176, v192
	v_mul_f32_e32 v205, s11, v129
	v_fma_f32 v129, v205, v177, v193
	v_cvt_pk_bf16_f32 v40, v114, v115
	v_cvt_pk_bf16_f32 v41, v116, v117
	v_cvt_pk_bf16_f32 v42, v118, v119
	v_cvt_pk_bf16_f32 v43, v120, v121
	v_cvt_pk_bf16_f32 v44, v122, v123
	v_cvt_pk_bf16_f32 v45, v124, v125
	v_cvt_pk_bf16_f32 v46, v126, v127
	v_cvt_pk_bf16_f32 v47, v128, v129
	global_store_dwordx2 v208, v[40:41], s[2:3]
	global_store_dwordx2 v208, v[42:43], s[2:3] offset:512
	global_store_dwordx2 v208, v[44:45], s[2:3] offset:1024
	global_store_dwordx2 v208, v[46:47], s[2:3] offset:1536
	s_add_u32 s2, s2, 0x60000
	s_addc_u32 s3, s3, 0
	global_load_dwordx4 v[98:101], v207, s[0:1]
	global_load_dwordx4 v[102:105], v207, s[0:1] offset:1024
	global_load_dwordx4 v[106:109], v207, s[0:1] offset:2048
	global_load_dwordx4 v[110:113], v207, s[0:1] offset:3072
	s_add_u32 s0, s0, 0xc0000
	s_addc_u32 s1, s1, 0
	global_load_dwordx4 v[114:117], v207, s[0:1]
	global_load_dwordx4 v[118:121], v207, s[0:1] offset:1024
	global_load_dwordx4 v[122:125], v207, s[0:1] offset:2048
	global_load_dwordx4 v[126:129], v207, s[0:1] offset:3072
	s_add_u32 s0, s0, 0xc0000
	s_addc_u32 s1, s1, 0
	s_waitcnt vmcnt(16)
	v_mul_f32_e32 v194, v130, v130
	v_mul_f32_e32 v195, v134, v134
	v_mul_f32_e32 v196, v138, v138
	v_mul_f32_e32 v197, v142, v142
	v_mul_f32_e32 v198, v146, v146
	v_mul_f32_e32 v199, v150, v150
	v_mul_f32_e32 v200, v154, v154
	v_mul_f32_e32 v201, v158, v158
	v_fmac_f32_e32 v194, v131, v131
	v_fmac_f32_e32 v195, v135, v135
	v_fmac_f32_e32 v196, v139, v139
	v_fmac_f32_e32 v197, v143, v143
	v_fmac_f32_e32 v198, v147, v147
	v_fmac_f32_e32 v199, v151, v151
	v_fmac_f32_e32 v200, v155, v155
	v_fmac_f32_e32 v201, v159, v159
	v_fmac_f32_e32 v194, v132, v132
	v_fmac_f32_e32 v195, v136, v136
	v_fmac_f32_e32 v196, v140, v140
	v_fmac_f32_e32 v197, v144, v144
	v_fmac_f32_e32 v198, v148, v148
	v_fmac_f32_e32 v199, v152, v152
	v_fmac_f32_e32 v200, v156, v156
	v_fmac_f32_e32 v201, v160, v160
	v_fmac_f32_e32 v194, v133, v133
	v_fmac_f32_e32 v195, v137, v137
	v_fmac_f32_e32 v196, v141, v141
	v_fmac_f32_e32 v197, v145, v145
	v_fmac_f32_e32 v198, v149, v149
	v_fmac_f32_e32 v199, v153, v153
	v_fmac_f32_e32 v200, v157, v157
	v_fmac_f32_e32 v201, v161, v161
	v_add_f32_e32 v194, v194, v195
	v_add_f32_e32 v196, v196, v197
	v_add_f32_e32 v198, v198, v199
	v_add_f32_e32 v200, v200, v201
	v_add_f32_e32 v202, v194, v196
	v_add_f32_e32 v203, v198, v200
	s_nop 0
	v_add_f32_dpp v202, v202, v202 quad_perm:[1,0,3,2] row_mask:0xf bank_mask:0xf
	v_add_f32_dpp v203, v203, v203 quad_perm:[1,0,3,2] row_mask:0xf bank_mask:0xf
	s_nop 0
	v_add_f32_dpp v202, v202, v202 quad_perm:[2,3,0,1] row_mask:0xf bank_mask:0xf
	v_add_f32_dpp v203, v203, v203 quad_perm:[2,3,0,1] row_mask:0xf bank_mask:0xf
	s_nop 0
	v_add_f32_dpp v202, v202, v202 row_half_mirror row_mask:0xf bank_mask:0xf
	v_add_f32_dpp v203, v203, v203 row_half_mirror row_mask:0xf bank_mask:0xf
	s_nop 0
	v_add_f32_dpp v202, v202, v202 row_mirror row_mask:0xf bank_mask:0xf
	v_add_f32_dpp v203, v203, v203 row_mirror row_mask:0xf bank_mask:0xf
	s_nop 0
	v_add_f32_dpp v202, v202, v202 row_bcast:15 row_mask:0xa bank_mask:0xf
	v_add_f32_dpp v203, v203, v203 row_bcast:15 row_mask:0xa bank_mask:0xf
	s_nop 0
	v_add_f32_dpp v202, v202, v202 row_bcast:31 row_mask:0xc bank_mask:0xf
	v_add_f32_dpp v203, v203, v203 row_bcast:31 row_mask:0xc bank_mask:0xf
	s_nop 0
	v_fma_f32 v202, v202, s22, v206
	v_fma_f32 v203, v203, s22, v206
	v_rsq_f32_e32 v202, v202
	v_rsq_f32_e32 v203, v203
	s_nop 0
	v_readlane_b32 s10, v202, 63
	v_readlane_b32 s11, v203, 63
	s_nop 1
	v_mul_f32_e32 v204, s10, v130
	v_fma_f32 v130, v204, v162, v178
	v_mul_f32_e32 v205, s10, v131
	v_fma_f32 v131, v205, v163, v179
	v_mul_f32_e32 v204, s10, v132
	v_fma_f32 v132, v204, v164, v180
	v_mul_f32_e32 v205, s10, v133
	v_fma_f32 v133, v205, v165, v181
	v_mul_f32_e32 v204, s10, v134
	v_fma_f32 v134, v204, v166, v182
	v_mul_f32_e32 v205, s10, v135
	v_fma_f32 v135, v205, v167, v183
	v_mul_f32_e32 v204, s10, v136
	v_fma_f32 v136, v204, v168, v184
	v_mul_f32_e32 v205, s10, v137
	v_fma_f32 v137, v205, v169, v185
	v_mul_f32_e32 v204, s10, v138
	v_fma_f32 v138, v204, v170, v186
	v_mul_f32_e32 v205, s10, v139
	v_fma_f32 v139, v205, v171, v187
	v_mul_f32_e32 v204, s10, v140
	v_fma_f32 v140, v204, v172, v188
	v_mul_f32_e32 v205, s10, v141
	v_fma_f32 v141, v205, v173, v189
	v_mul_f32_e32 v204, s10, v142
	v_fma_f32 v142, v204, v174, v190
	v_mul_f32_e32 v205, s10, v143
	v_fma_f32 v143, v205, v175, v191
	v_mul_f32_e32 v204, s10, v144
	v_fma_f32 v144, v204, v176, v192
	v_mul_f32_e32 v205, s10, v145
	v_fma_f32 v145, v205, v177, v193
	v_cvt_pk_bf16_f32 v214, v130, v131
	v_cvt_pk_bf16_f32 v215, v132, v133
	v_cvt_pk_bf16_f32 v216, v134, v135
	v_cvt_pk_bf16_f32 v217, v136, v137
	v_cvt_pk_bf16_f32 v218, v138, v139
	v_cvt_pk_bf16_f32 v219, v140, v141
	v_cvt_pk_bf16_f32 v220, v142, v143
	v_cvt_pk_bf16_f32 v221, v144, v145
	global_store_dwordx2 v208, v[214:215], s[2:3]
	global_store_dwordx2 v208, v[216:217], s[2:3] offset:512
	global_store_dwordx2 v208, v[218:219], s[2:3] offset:1024
	global_store_dwordx2 v208, v[220:221], s[2:3] offset:1536
	s_add_u32 s2, s2, 0x60000
	s_addc_u32 s3, s3, 0
	v_mul_f32_e32 v204, s11, v146
	v_fma_f32 v146, v204, v162, v178
	v_mul_f32_e32 v205, s11, v147
	v_fma_f32 v147, v205, v163, v179
	v_mul_f32_e32 v204, s11, v148
	v_fma_f32 v148, v204, v164, v180
	v_mul_f32_e32 v205, s11, v149
	v_fma_f32 v149, v205, v165, v181
	v_mul_f32_e32 v204, s11, v150
	v_fma_f32 v150, v204, v166, v182
	v_mul_f32_e32 v205, s11, v151
	v_fma_f32 v151, v205, v167, v183
	v_mul_f32_e32 v204, s11, v152
	v_fma_f32 v152, v204, v168, v184
	v_mul_f32_e32 v205, s11, v153
	v_fma_f32 v153, v205, v169, v185
	v_mul_f32_e32 v204, s11, v154
	v_fma_f32 v154, v204, v170, v186
	v_mul_f32_e32 v205, s11, v155
	v_fma_f32 v155, v205, v171, v187
	v_mul_f32_e32 v204, s11, v156
	v_fma_f32 v156, v204, v172, v188
	v_mul_f32_e32 v205, s11, v157
	v_fma_f32 v157, v205, v173, v189
	v_mul_f32_e32 v204, s11, v158
	v_fma_f32 v158, v204, v174, v190
	v_mul_f32_e32 v205, s11, v159
	v_fma_f32 v159, v205, v175, v191
	v_mul_f32_e32 v204, s11, v160
	v_fma_f32 v160, v204, v176, v192
	v_mul_f32_e32 v205, s11, v161
	v_fma_f32 v161, v205, v177, v193
	v_cvt_pk_bf16_f32 v40, v146, v147
	v_cvt_pk_bf16_f32 v41, v148, v149
	v_cvt_pk_bf16_f32 v42, v150, v151
	v_cvt_pk_bf16_f32 v43, v152, v153
	v_cvt_pk_bf16_f32 v44, v154, v155
	v_cvt_pk_bf16_f32 v45, v156, v157
	v_cvt_pk_bf16_f32 v46, v158, v159
	v_cvt_pk_bf16_f32 v47, v160, v161
	global_store_dwordx2 v208, v[40:41], s[2:3]
	global_store_dwordx2 v208, v[42:43], s[2:3] offset:512
	global_store_dwordx2 v208, v[44:45], s[2:3] offset:1024
	global_store_dwordx2 v208, v[46:47], s[2:3] offset:1536
	s_add_u32 s2, s2, 0x60000
	s_addc_u32 s3, s3, 0
	global_load_dwordx4 v[130:133], v207, s[0:1]
	global_load_dwordx4 v[134:137], v207, s[0:1] offset:1024
	global_load_dwordx4 v[138:141], v207, s[0:1] offset:2048
	global_load_dwordx4 v[142:145], v207, s[0:1] offset:3072
	s_add_u32 s0, s0, 0xc0000
	s_addc_u32 s1, s1, 0
	global_load_dwordx4 v[146:149], v207, s[0:1]
	global_load_dwordx4 v[150:153], v207, s[0:1] offset:1024
	global_load_dwordx4 v[154:157], v207, s[0:1] offset:2048
	global_load_dwordx4 v[158:161], v207, s[0:1] offset:3072
	s_add_u32 s0, s0, 0xc0000
	s_addc_u32 s1, s1, 0
	s_waitcnt vmcnt(16)
	v_mul_f32_e32 v194, v98, v98
	v_mul_f32_e32 v195, v102, v102
	v_mul_f32_e32 v196, v106, v106
	v_mul_f32_e32 v197, v110, v110
	v_mul_f32_e32 v198, v114, v114
	v_mul_f32_e32 v199, v118, v118
	v_mul_f32_e32 v200, v122, v122
	v_mul_f32_e32 v201, v126, v126
	v_fmac_f32_e32 v194, v99, v99
	v_fmac_f32_e32 v195, v103, v103
	v_fmac_f32_e32 v196, v107, v107
	v_fmac_f32_e32 v197, v111, v111
	v_fmac_f32_e32 v198, v115, v115
	v_fmac_f32_e32 v199, v119, v119
	v_fmac_f32_e32 v200, v123, v123
	v_fmac_f32_e32 v201, v127, v127
	v_fmac_f32_e32 v194, v100, v100
	v_fmac_f32_e32 v195, v104, v104
	v_fmac_f32_e32 v196, v108, v108
	v_fmac_f32_e32 v197, v112, v112
	v_fmac_f32_e32 v198, v116, v116
	v_fmac_f32_e32 v199, v120, v120
	v_fmac_f32_e32 v200, v124, v124
	v_fmac_f32_e32 v201, v128, v128
	v_fmac_f32_e32 v194, v101, v101
	v_fmac_f32_e32 v195, v105, v105
	v_fmac_f32_e32 v196, v109, v109
	v_fmac_f32_e32 v197, v113, v113
	v_fmac_f32_e32 v198, v117, v117
	v_fmac_f32_e32 v199, v121, v121
	v_fmac_f32_e32 v200, v125, v125
	v_fmac_f32_e32 v201, v129, v129
	v_add_f32_e32 v194, v194, v195
	v_add_f32_e32 v196, v196, v197
	v_add_f32_e32 v198, v198, v199
	v_add_f32_e32 v200, v200, v201
	v_add_f32_e32 v202, v194, v196
	v_add_f32_e32 v203, v198, v200
	s_nop 0
	v_add_f32_dpp v202, v202, v202 quad_perm:[1,0,3,2] row_mask:0xf bank_mask:0xf
	v_add_f32_dpp v203, v203, v203 quad_perm:[1,0,3,2] row_mask:0xf bank_mask:0xf
	s_nop 0
	v_add_f32_dpp v202, v202, v202 quad_perm:[2,3,0,1] row_mask:0xf bank_mask:0xf
	v_add_f32_dpp v203, v203, v203 quad_perm:[2,3,0,1] row_mask:0xf bank_mask:0xf
	s_nop 0
	v_add_f32_dpp v202, v202, v202 row_half_mirror row_mask:0xf bank_mask:0xf
	v_add_f32_dpp v203, v203, v203 row_half_mirror row_mask:0xf bank_mask:0xf
	s_nop 0
	v_add_f32_dpp v202, v202, v202 row_mirror row_mask:0xf bank_mask:0xf
	v_add_f32_dpp v203, v203, v203 row_mirror row_mask:0xf bank_mask:0xf
	s_nop 0
	v_add_f32_dpp v202, v202, v202 row_bcast:15 row_mask:0xa bank_mask:0xf
	v_add_f32_dpp v203, v203, v203 row_bcast:15 row_mask:0xa bank_mask:0xf
	s_nop 0
	v_add_f32_dpp v202, v202, v202 row_bcast:31 row_mask:0xc bank_mask:0xf
	v_add_f32_dpp v203, v203, v203 row_bcast:31 row_mask:0xc bank_mask:0xf
	s_nop 0
	v_fma_f32 v202, v202, s22, v206
	v_fma_f32 v203, v203, s22, v206
	v_rsq_f32_e32 v202, v202
	v_rsq_f32_e32 v203, v203
	s_nop 0
	v_readlane_b32 s10, v202, 63
	v_readlane_b32 s11, v203, 63
	s_nop 1
	v_mul_f32_e32 v204, s10, v98
	v_fma_f32 v98, v204, v162, v178
	v_mul_f32_e32 v205, s10, v99
	v_fma_f32 v99, v205, v163, v179
	v_mul_f32_e32 v204, s10, v100
	v_fma_f32 v100, v204, v164, v180
	v_mul_f32_e32 v205, s10, v101
	v_fma_f32 v101, v205, v165, v181
	v_mul_f32_e32 v204, s10, v102
	v_fma_f32 v102, v204, v166, v182
	v_mul_f32_e32 v205, s10, v103
	v_fma_f32 v103, v205, v167, v183
	v_mul_f32_e32 v204, s10, v104
	v_fma_f32 v104, v204, v168, v184
	v_mul_f32_e32 v205, s10, v105
	v_fma_f32 v105, v205, v169, v185
	v_mul_f32_e32 v204, s10, v106
	v_fma_f32 v106, v204, v170, v186
	v_mul_f32_e32 v205, s10, v107
	v_fma_f32 v107, v205, v171, v187
	v_mul_f32_e32 v204, s10, v108
	v_fma_f32 v108, v204, v172, v188
	v_mul_f32_e32 v205, s10, v109
	v_fma_f32 v109, v205, v173, v189
	v_mul_f32_e32 v204, s10, v110
	v_fma_f32 v110, v204, v174, v190
	v_mul_f32_e32 v205, s10, v111
	v_fma_f32 v111, v205, v175, v191
	v_mul_f32_e32 v204, s10, v112
	v_fma_f32 v112, v204, v176, v192
	v_mul_f32_e32 v205, s10, v113
	v_fma_f32 v113, v205, v177, v193
	v_cvt_pk_bf16_f32 v214, v98, v99
	v_cvt_pk_bf16_f32 v215, v100, v101
	v_cvt_pk_bf16_f32 v216, v102, v103
	v_cvt_pk_bf16_f32 v217, v104, v105
	v_cvt_pk_bf16_f32 v218, v106, v107
	v_cvt_pk_bf16_f32 v219, v108, v109
	v_cvt_pk_bf16_f32 v220, v110, v111
	v_cvt_pk_bf16_f32 v221, v112, v113
	global_store_dwordx2 v208, v[214:215], s[2:3]
	global_store_dwordx2 v208, v[216:217], s[2:3] offset:512
	global_store_dwordx2 v208, v[218:219], s[2:3] offset:1024
	global_store_dwordx2 v208, v[220:221], s[2:3] offset:1536
	s_add_u32 s2, s2, 0x60000
	s_addc_u32 s3, s3, 0
	v_mul_f32_e32 v204, s11, v114
	v_fma_f32 v114, v204, v162, v178
	v_mul_f32_e32 v205, s11, v115
	v_fma_f32 v115, v205, v163, v179
	v_mul_f32_e32 v204, s11, v116
	v_fma_f32 v116, v204, v164, v180
	v_mul_f32_e32 v205, s11, v117
	v_fma_f32 v117, v205, v165, v181
	v_mul_f32_e32 v204, s11, v118
	v_fma_f32 v118, v204, v166, v182
	v_mul_f32_e32 v205, s11, v119
	v_fma_f32 v119, v205, v167, v183
	v_mul_f32_e32 v204, s11, v120
	v_fma_f32 v120, v204, v168, v184
	v_mul_f32_e32 v205, s11, v121
	v_fma_f32 v121, v205, v169, v185
	v_mul_f32_e32 v204, s11, v122
	v_fma_f32 v122, v204, v170, v186
	v_mul_f32_e32 v205, s11, v123
	v_fma_f32 v123, v205, v171, v187
	v_mul_f32_e32 v204, s11, v124
	v_fma_f32 v124, v204, v172, v188
	v_mul_f32_e32 v205, s11, v125
	v_fma_f32 v125, v205, v173, v189
	v_mul_f32_e32 v204, s11, v126
	v_fma_f32 v126, v204, v174, v190
	v_mul_f32_e32 v205, s11, v127
	v_fma_f32 v127, v205, v175, v191
	v_mul_f32_e32 v204, s11, v128
	v_fma_f32 v128, v204, v176, v192
	v_mul_f32_e32 v205, s11, v129
	v_fma_f32 v129, v205, v177, v193
	v_cvt_pk_bf16_f32 v40, v114, v115
	v_cvt_pk_bf16_f32 v41, v116, v117
	v_cvt_pk_bf16_f32 v42, v118, v119
	v_cvt_pk_bf16_f32 v43, v120, v121
	v_cvt_pk_bf16_f32 v44, v122, v123
	v_cvt_pk_bf16_f32 v45, v124, v125
	v_cvt_pk_bf16_f32 v46, v126, v127
	v_cvt_pk_bf16_f32 v47, v128, v129
	global_store_dwordx2 v208, v[40:41], s[2:3]
	global_store_dwordx2 v208, v[42:43], s[2:3] offset:512
	global_store_dwordx2 v208, v[44:45], s[2:3] offset:1024
	global_store_dwordx2 v208, v[46:47], s[2:3] offset:1536
	s_add_u32 s2, s2, 0x60000
	s_addc_u32 s3, s3, 0
	global_load_dwordx4 v[98:101], v207, s[0:1]
	global_load_dwordx4 v[102:105], v207, s[0:1] offset:1024
	global_load_dwordx4 v[106:109], v207, s[0:1] offset:2048
	global_load_dwordx4 v[110:113], v207, s[0:1] offset:3072
	s_add_u32 s0, s0, 0xc0000
	s_addc_u32 s1, s1, 0
	global_load_dwordx4 v[114:117], v207, s[0:1]
	global_load_dwordx4 v[118:121], v207, s[0:1] offset:1024
	global_load_dwordx4 v[122:125], v207, s[0:1] offset:2048
	global_load_dwordx4 v[126:129], v207, s[0:1] offset:3072
	s_add_u32 s0, s0, 0xc0000
	s_addc_u32 s1, s1, 0
	s_waitcnt vmcnt(16)
	v_mul_f32_e32 v194, v130, v130
	v_mul_f32_e32 v195, v134, v134
	v_mul_f32_e32 v196, v138, v138
	v_mul_f32_e32 v197, v142, v142
	v_mul_f32_e32 v198, v146, v146
	v_mul_f32_e32 v199, v150, v150
	v_mul_f32_e32 v200, v154, v154
	v_mul_f32_e32 v201, v158, v158
	v_fmac_f32_e32 v194, v131, v131
	v_fmac_f32_e32 v195, v135, v135
	v_fmac_f32_e32 v196, v139, v139
	v_fmac_f32_e32 v197, v143, v143
	v_fmac_f32_e32 v198, v147, v147
	v_fmac_f32_e32 v199, v151, v151
	v_fmac_f32_e32 v200, v155, v155
	v_fmac_f32_e32 v201, v159, v159
	v_fmac_f32_e32 v194, v132, v132
	v_fmac_f32_e32 v195, v136, v136
	v_fmac_f32_e32 v196, v140, v140
	v_fmac_f32_e32 v197, v144, v144
	v_fmac_f32_e32 v198, v148, v148
	v_fmac_f32_e32 v199, v152, v152
	v_fmac_f32_e32 v200, v156, v156
	v_fmac_f32_e32 v201, v160, v160
	v_fmac_f32_e32 v194, v133, v133
	v_fmac_f32_e32 v195, v137, v137
	v_fmac_f32_e32 v196, v141, v141
	v_fmac_f32_e32 v197, v145, v145
	v_fmac_f32_e32 v198, v149, v149
	v_fmac_f32_e32 v199, v153, v153
	v_fmac_f32_e32 v200, v157, v157
	v_fmac_f32_e32 v201, v161, v161
	v_add_f32_e32 v194, v194, v195
	v_add_f32_e32 v196, v196, v197
	v_add_f32_e32 v198, v198, v199
	v_add_f32_e32 v200, v200, v201
	v_add_f32_e32 v202, v194, v196
	v_add_f32_e32 v203, v198, v200
	s_nop 0
	v_add_f32_dpp v202, v202, v202 quad_perm:[1,0,3,2] row_mask:0xf bank_mask:0xf
	v_add_f32_dpp v203, v203, v203 quad_perm:[1,0,3,2] row_mask:0xf bank_mask:0xf
	s_nop 0
	v_add_f32_dpp v202, v202, v202 quad_perm:[2,3,0,1] row_mask:0xf bank_mask:0xf
	v_add_f32_dpp v203, v203, v203 quad_perm:[2,3,0,1] row_mask:0xf bank_mask:0xf
	s_nop 0
	v_add_f32_dpp v202, v202, v202 row_half_mirror row_mask:0xf bank_mask:0xf
	v_add_f32_dpp v203, v203, v203 row_half_mirror row_mask:0xf bank_mask:0xf
	s_nop 0
	v_add_f32_dpp v202, v202, v202 row_mirror row_mask:0xf bank_mask:0xf
	v_add_f32_dpp v203, v203, v203 row_mirror row_mask:0xf bank_mask:0xf
	s_nop 0
	v_add_f32_dpp v202, v202, v202 row_bcast:15 row_mask:0xa bank_mask:0xf
	v_add_f32_dpp v203, v203, v203 row_bcast:15 row_mask:0xa bank_mask:0xf
	s_nop 0
	v_add_f32_dpp v202, v202, v202 row_bcast:31 row_mask:0xc bank_mask:0xf
	v_add_f32_dpp v203, v203, v203 row_bcast:31 row_mask:0xc bank_mask:0xf
	s_nop 0
	v_fma_f32 v202, v202, s22, v206
	v_fma_f32 v203, v203, s22, v206
	v_rsq_f32_e32 v202, v202
	v_rsq_f32_e32 v203, v203
	s_nop 0
	v_readlane_b32 s10, v202, 63
	v_readlane_b32 s11, v203, 63
	s_nop 1
	v_mul_f32_e32 v204, s10, v130
	v_fma_f32 v130, v204, v162, v178
	v_mul_f32_e32 v205, s10, v131
	v_fma_f32 v131, v205, v163, v179
	v_mul_f32_e32 v204, s10, v132
	v_fma_f32 v132, v204, v164, v180
	v_mul_f32_e32 v205, s10, v133
	v_fma_f32 v133, v205, v165, v181
	v_mul_f32_e32 v204, s10, v134
	v_fma_f32 v134, v204, v166, v182
	v_mul_f32_e32 v205, s10, v135
	v_fma_f32 v135, v205, v167, v183
	v_mul_f32_e32 v204, s10, v136
	v_fma_f32 v136, v204, v168, v184
	v_mul_f32_e32 v205, s10, v137
	v_fma_f32 v137, v205, v169, v185
	v_mul_f32_e32 v204, s10, v138
	v_fma_f32 v138, v204, v170, v186
	v_mul_f32_e32 v205, s10, v139
	v_fma_f32 v139, v205, v171, v187
	v_mul_f32_e32 v204, s10, v140
	v_fma_f32 v140, v204, v172, v188
	v_mul_f32_e32 v205, s10, v141
	v_fma_f32 v141, v205, v173, v189
	v_mul_f32_e32 v204, s10, v142
	v_fma_f32 v142, v204, v174, v190
	v_mul_f32_e32 v205, s10, v143
	v_fma_f32 v143, v205, v175, v191
	v_mul_f32_e32 v204, s10, v144
	v_fma_f32 v144, v204, v176, v192
	v_mul_f32_e32 v205, s10, v145
	v_fma_f32 v145, v205, v177, v193
	v_cvt_pk_bf16_f32 v214, v130, v131
	v_cvt_pk_bf16_f32 v215, v132, v133
	v_cvt_pk_bf16_f32 v216, v134, v135
	v_cvt_pk_bf16_f32 v217, v136, v137
	v_cvt_pk_bf16_f32 v218, v138, v139
	v_cvt_pk_bf16_f32 v219, v140, v141
	v_cvt_pk_bf16_f32 v220, v142, v143
	v_cvt_pk_bf16_f32 v221, v144, v145
	global_store_dwordx2 v208, v[214:215], s[2:3]
	global_store_dwordx2 v208, v[216:217], s[2:3] offset:512
	global_store_dwordx2 v208, v[218:219], s[2:3] offset:1024
	global_store_dwordx2 v208, v[220:221], s[2:3] offset:1536
	s_add_u32 s2, s2, 0x60000
	s_addc_u32 s3, s3, 0
	v_mul_f32_e32 v204, s11, v146
	v_fma_f32 v146, v204, v162, v178
	v_mul_f32_e32 v205, s11, v147
	v_fma_f32 v147, v205, v163, v179
	v_mul_f32_e32 v204, s11, v148
	v_fma_f32 v148, v204, v164, v180
	v_mul_f32_e32 v205, s11, v149
	v_fma_f32 v149, v205, v165, v181
	v_mul_f32_e32 v204, s11, v150
	v_fma_f32 v150, v204, v166, v182
	v_mul_f32_e32 v205, s11, v151
	v_fma_f32 v151, v205, v167, v183
	v_mul_f32_e32 v204, s11, v152
	v_fma_f32 v152, v204, v168, v184
	v_mul_f32_e32 v205, s11, v153
	v_fma_f32 v153, v205, v169, v185
	v_mul_f32_e32 v204, s11, v154
	v_fma_f32 v154, v204, v170, v186
	v_mul_f32_e32 v205, s11, v155
	v_fma_f32 v155, v205, v171, v187
	v_mul_f32_e32 v204, s11, v156
	v_fma_f32 v156, v204, v172, v188
	v_mul_f32_e32 v205, s11, v157
	v_fma_f32 v157, v205, v173, v189
	v_mul_f32_e32 v204, s11, v158
	v_fma_f32 v158, v204, v174, v190
	v_mul_f32_e32 v205, s11, v159
	v_fma_f32 v159, v205, v175, v191
	v_mul_f32_e32 v204, s11, v160
	v_fma_f32 v160, v204, v176, v192
	v_mul_f32_e32 v205, s11, v161
	v_fma_f32 v161, v205, v177, v193
	v_cvt_pk_bf16_f32 v40, v146, v147
	v_cvt_pk_bf16_f32 v41, v148, v149
	v_cvt_pk_bf16_f32 v42, v150, v151
	v_cvt_pk_bf16_f32 v43, v152, v153
	v_cvt_pk_bf16_f32 v44, v154, v155
	v_cvt_pk_bf16_f32 v45, v156, v157
	v_cvt_pk_bf16_f32 v46, v158, v159
	v_cvt_pk_bf16_f32 v47, v160, v161
	global_store_dwordx2 v208, v[40:41], s[2:3]
	global_store_dwordx2 v208, v[42:43], s[2:3] offset:512
	global_store_dwordx2 v208, v[44:45], s[2:3] offset:1024
	global_store_dwordx2 v208, v[46:47], s[2:3] offset:1536
	s_add_u32 s2, s2, 0x60000
	s_addc_u32 s3, s3, 0
	global_load_dwordx4 v[130:133], v207, s[0:1]
	global_load_dwordx4 v[134:137], v207, s[0:1] offset:1024
	global_load_dwordx4 v[138:141], v207, s[0:1] offset:2048
	global_load_dwordx4 v[142:145], v207, s[0:1] offset:3072
	s_add_u32 s0, s0, 0xc0000
	s_addc_u32 s1, s1, 0
	global_load_dwordx4 v[146:149], v207, s[0:1]
	global_load_dwordx4 v[150:153], v207, s[0:1] offset:1024
	global_load_dwordx4 v[154:157], v207, s[0:1] offset:2048
	global_load_dwordx4 v[158:161], v207, s[0:1] offset:3072
	s_add_u32 s0, s0, 0xc0000
	s_addc_u32 s1, s1, 0
	s_waitcnt vmcnt(16)
	v_mul_f32_e32 v194, v98, v98
	v_mul_f32_e32 v195, v102, v102
	v_mul_f32_e32 v196, v106, v106
	v_mul_f32_e32 v197, v110, v110
	v_mul_f32_e32 v198, v114, v114
	v_mul_f32_e32 v199, v118, v118
	v_mul_f32_e32 v200, v122, v122
	v_mul_f32_e32 v201, v126, v126
	v_fmac_f32_e32 v194, v99, v99
	v_fmac_f32_e32 v195, v103, v103
	v_fmac_f32_e32 v196, v107, v107
	v_fmac_f32_e32 v197, v111, v111
	v_fmac_f32_e32 v198, v115, v115
	v_fmac_f32_e32 v199, v119, v119
	v_fmac_f32_e32 v200, v123, v123
	v_fmac_f32_e32 v201, v127, v127
	v_fmac_f32_e32 v194, v100, v100
	v_fmac_f32_e32 v195, v104, v104
	v_fmac_f32_e32 v196, v108, v108
	v_fmac_f32_e32 v197, v112, v112
	v_fmac_f32_e32 v198, v116, v116
	v_fmac_f32_e32 v199, v120, v120
	v_fmac_f32_e32 v200, v124, v124
	v_fmac_f32_e32 v201, v128, v128
	v_fmac_f32_e32 v194, v101, v101
	v_fmac_f32_e32 v195, v105, v105
	v_fmac_f32_e32 v196, v109, v109
	v_fmac_f32_e32 v197, v113, v113
	v_fmac_f32_e32 v198, v117, v117
	v_fmac_f32_e32 v199, v121, v121
	v_fmac_f32_e32 v200, v125, v125
	v_fmac_f32_e32 v201, v129, v129
	v_add_f32_e32 v194, v194, v195
	v_add_f32_e32 v196, v196, v197
	v_add_f32_e32 v198, v198, v199
	v_add_f32_e32 v200, v200, v201
	v_add_f32_e32 v202, v194, v196
	v_add_f32_e32 v203, v198, v200
	s_nop 0
	v_add_f32_dpp v202, v202, v202 quad_perm:[1,0,3,2] row_mask:0xf bank_mask:0xf
	v_add_f32_dpp v203, v203, v203 quad_perm:[1,0,3,2] row_mask:0xf bank_mask:0xf
	s_nop 0
	v_add_f32_dpp v202, v202, v202 quad_perm:[2,3,0,1] row_mask:0xf bank_mask:0xf
	v_add_f32_dpp v203, v203, v203 quad_perm:[2,3,0,1] row_mask:0xf bank_mask:0xf
	s_nop 0
	v_add_f32_dpp v202, v202, v202 row_half_mirror row_mask:0xf bank_mask:0xf
	v_add_f32_dpp v203, v203, v203 row_half_mirror row_mask:0xf bank_mask:0xf
	s_nop 0
	v_add_f32_dpp v202, v202, v202 row_mirror row_mask:0xf bank_mask:0xf
	v_add_f32_dpp v203, v203, v203 row_mirror row_mask:0xf bank_mask:0xf
	s_nop 0
	v_add_f32_dpp v202, v202, v202 row_bcast:15 row_mask:0xa bank_mask:0xf
	v_add_f32_dpp v203, v203, v203 row_bcast:15 row_mask:0xa bank_mask:0xf
	s_nop 0
	v_add_f32_dpp v202, v202, v202 row_bcast:31 row_mask:0xc bank_mask:0xf
	v_add_f32_dpp v203, v203, v203 row_bcast:31 row_mask:0xc bank_mask:0xf
	s_nop 0
	v_fma_f32 v202, v202, s22, v206
	v_fma_f32 v203, v203, s22, v206
	v_rsq_f32_e32 v202, v202
	v_rsq_f32_e32 v203, v203
	s_nop 0
	v_readlane_b32 s10, v202, 63
	v_readlane_b32 s11, v203, 63
	s_nop 1
	v_mul_f32_e32 v204, s10, v98
	v_fma_f32 v98, v204, v162, v178
	v_mul_f32_e32 v205, s10, v99
	v_fma_f32 v99, v205, v163, v179
	v_mul_f32_e32 v204, s10, v100
	v_fma_f32 v100, v204, v164, v180
	v_mul_f32_e32 v205, s10, v101
	v_fma_f32 v101, v205, v165, v181
	v_mul_f32_e32 v204, s10, v102
	v_fma_f32 v102, v204, v166, v182
	v_mul_f32_e32 v205, s10, v103
	v_fma_f32 v103, v205, v167, v183
	v_mul_f32_e32 v204, s10, v104
	v_fma_f32 v104, v204, v168, v184
	v_mul_f32_e32 v205, s10, v105
	v_fma_f32 v105, v205, v169, v185
	v_mul_f32_e32 v204, s10, v106
	v_fma_f32 v106, v204, v170, v186
	v_mul_f32_e32 v205, s10, v107
	v_fma_f32 v107, v205, v171, v187
	v_mul_f32_e32 v204, s10, v108
	v_fma_f32 v108, v204, v172, v188
	v_mul_f32_e32 v205, s10, v109
	v_fma_f32 v109, v205, v173, v189
	v_mul_f32_e32 v204, s10, v110
	v_fma_f32 v110, v204, v174, v190
	v_mul_f32_e32 v205, s10, v111
	v_fma_f32 v111, v205, v175, v191
	v_mul_f32_e32 v204, s10, v112
	v_fma_f32 v112, v204, v176, v192
	v_mul_f32_e32 v205, s10, v113
	v_fma_f32 v113, v205, v177, v193
	v_cvt_pk_bf16_f32 v214, v98, v99
	v_cvt_pk_bf16_f32 v215, v100, v101
	v_cvt_pk_bf16_f32 v216, v102, v103
	v_cvt_pk_bf16_f32 v217, v104, v105
	v_cvt_pk_bf16_f32 v218, v106, v107
	v_cvt_pk_bf16_f32 v219, v108, v109
	v_cvt_pk_bf16_f32 v220, v110, v111
	v_cvt_pk_bf16_f32 v221, v112, v113
	global_store_dwordx2 v208, v[214:215], s[2:3]
	global_store_dwordx2 v208, v[216:217], s[2:3] offset:512
	global_store_dwordx2 v208, v[218:219], s[2:3] offset:1024
	global_store_dwordx2 v208, v[220:221], s[2:3] offset:1536
	s_add_u32 s2, s2, 0x60000
	s_addc_u32 s3, s3, 0
	v_mul_f32_e32 v204, s11, v114
	v_fma_f32 v114, v204, v162, v178
	v_mul_f32_e32 v205, s11, v115
	v_fma_f32 v115, v205, v163, v179
	v_mul_f32_e32 v204, s11, v116
	v_fma_f32 v116, v204, v164, v180
	v_mul_f32_e32 v205, s11, v117
	v_fma_f32 v117, v205, v165, v181
	v_mul_f32_e32 v204, s11, v118
	v_fma_f32 v118, v204, v166, v182
	v_mul_f32_e32 v205, s11, v119
	v_fma_f32 v119, v205, v167, v183
	v_mul_f32_e32 v204, s11, v120
	v_fma_f32 v120, v204, v168, v184
	v_mul_f32_e32 v205, s11, v121
	v_fma_f32 v121, v205, v169, v185
	v_mul_f32_e32 v204, s11, v122
	v_fma_f32 v122, v204, v170, v186
	v_mul_f32_e32 v205, s11, v123
	v_fma_f32 v123, v205, v171, v187
	v_mul_f32_e32 v204, s11, v124
	v_fma_f32 v124, v204, v172, v188
	v_mul_f32_e32 v205, s11, v125
	v_fma_f32 v125, v205, v173, v189
	v_mul_f32_e32 v204, s11, v126
	v_fma_f32 v126, v204, v174, v190
	v_mul_f32_e32 v205, s11, v127
	v_fma_f32 v127, v205, v175, v191
	v_mul_f32_e32 v204, s11, v128
	v_fma_f32 v128, v204, v176, v192
	v_mul_f32_e32 v205, s11, v129
	v_fma_f32 v129, v205, v177, v193
	v_cvt_pk_bf16_f32 v40, v114, v115
	v_cvt_pk_bf16_f32 v41, v116, v117
	v_cvt_pk_bf16_f32 v42, v118, v119
	v_cvt_pk_bf16_f32 v43, v120, v121
	v_cvt_pk_bf16_f32 v44, v122, v123
	v_cvt_pk_bf16_f32 v45, v124, v125
	v_cvt_pk_bf16_f32 v46, v126, v127
	v_cvt_pk_bf16_f32 v47, v128, v129
	global_store_dwordx2 v208, v[40:41], s[2:3]
	global_store_dwordx2 v208, v[42:43], s[2:3] offset:512
	global_store_dwordx2 v208, v[44:45], s[2:3] offset:1024
	global_store_dwordx2 v208, v[46:47], s[2:3] offset:1536
	s_add_u32 s2, s2, 0x60000
	s_addc_u32 s3, s3, 0
	global_load_dwordx4 v[98:101], v207, s[0:1]
	global_load_dwordx4 v[102:105], v207, s[0:1] offset:1024
	global_load_dwordx4 v[106:109], v207, s[0:1] offset:2048
	global_load_dwordx4 v[110:113], v207, s[0:1] offset:3072
	s_add_u32 s0, s0, 0xc0000
	s_addc_u32 s1, s1, 0
	global_load_dwordx4 v[114:117], v207, s[0:1]
	global_load_dwordx4 v[118:121], v207, s[0:1] offset:1024
	global_load_dwordx4 v[122:125], v207, s[0:1] offset:2048
	global_load_dwordx4 v[126:129], v207, s[0:1] offset:3072
	s_add_u32 s0, s0, 0xc0000
	s_addc_u32 s1, s1, 0
	s_waitcnt vmcnt(16)
	v_mul_f32_e32 v194, v130, v130
	v_mul_f32_e32 v195, v134, v134
	v_mul_f32_e32 v196, v138, v138
	v_mul_f32_e32 v197, v142, v142
	v_mul_f32_e32 v198, v146, v146
	v_mul_f32_e32 v199, v150, v150
	v_mul_f32_e32 v200, v154, v154
	v_mul_f32_e32 v201, v158, v158
	v_fmac_f32_e32 v194, v131, v131
	v_fmac_f32_e32 v195, v135, v135
	v_fmac_f32_e32 v196, v139, v139
	v_fmac_f32_e32 v197, v143, v143
	v_fmac_f32_e32 v198, v147, v147
	v_fmac_f32_e32 v199, v151, v151
	v_fmac_f32_e32 v200, v155, v155
	v_fmac_f32_e32 v201, v159, v159
	v_fmac_f32_e32 v194, v132, v132
	v_fmac_f32_e32 v195, v136, v136
	v_fmac_f32_e32 v196, v140, v140
	v_fmac_f32_e32 v197, v144, v144
	v_fmac_f32_e32 v198, v148, v148
	v_fmac_f32_e32 v199, v152, v152
	v_fmac_f32_e32 v200, v156, v156
	v_fmac_f32_e32 v201, v160, v160
	v_fmac_f32_e32 v194, v133, v133
	v_fmac_f32_e32 v195, v137, v137
	v_fmac_f32_e32 v196, v141, v141
	v_fmac_f32_e32 v197, v145, v145
	v_fmac_f32_e32 v198, v149, v149
	v_fmac_f32_e32 v199, v153, v153
	v_fmac_f32_e32 v200, v157, v157
	v_fmac_f32_e32 v201, v161, v161
	v_add_f32_e32 v194, v194, v195
	v_add_f32_e32 v196, v196, v197
	v_add_f32_e32 v198, v198, v199
	v_add_f32_e32 v200, v200, v201
	v_add_f32_e32 v202, v194, v196
	v_add_f32_e32 v203, v198, v200
	s_nop 0
	v_add_f32_dpp v202, v202, v202 quad_perm:[1,0,3,2] row_mask:0xf bank_mask:0xf
	v_add_f32_dpp v203, v203, v203 quad_perm:[1,0,3,2] row_mask:0xf bank_mask:0xf
	s_nop 0
	v_add_f32_dpp v202, v202, v202 quad_perm:[2,3,0,1] row_mask:0xf bank_mask:0xf
	v_add_f32_dpp v203, v203, v203 quad_perm:[2,3,0,1] row_mask:0xf bank_mask:0xf
	s_nop 0
	v_add_f32_dpp v202, v202, v202 row_half_mirror row_mask:0xf bank_mask:0xf
	v_add_f32_dpp v203, v203, v203 row_half_mirror row_mask:0xf bank_mask:0xf
	s_nop 0
	v_add_f32_dpp v202, v202, v202 row_mirror row_mask:0xf bank_mask:0xf
	v_add_f32_dpp v203, v203, v203 row_mirror row_mask:0xf bank_mask:0xf
	s_nop 0
	v_add_f32_dpp v202, v202, v202 row_bcast:15 row_mask:0xa bank_mask:0xf
	v_add_f32_dpp v203, v203, v203 row_bcast:15 row_mask:0xa bank_mask:0xf
	s_nop 0
	v_add_f32_dpp v202, v202, v202 row_bcast:31 row_mask:0xc bank_mask:0xf
	v_add_f32_dpp v203, v203, v203 row_bcast:31 row_mask:0xc bank_mask:0xf
	s_nop 0
	v_fma_f32 v202, v202, s22, v206
	v_fma_f32 v203, v203, s22, v206
	v_rsq_f32_e32 v202, v202
	v_rsq_f32_e32 v203, v203
	s_nop 0
	v_readlane_b32 s10, v202, 63
	v_readlane_b32 s11, v203, 63
	s_nop 1
	s_cmp_lt_u32 s5, 0x80
	s_cbranch_scc1 .Ln2_r10_b0
	v_mul_f32_e32 v204, s10, v130
	v_fma_f32 v130, v204, v222, v238
	v_mul_f32_e32 v205, s10, v131
	v_fma_f32 v131, v205, v223, v239
	v_mul_f32_e32 v204, s10, v132
	v_fma_f32 v132, v204, v224, v240
	v_mul_f32_e32 v205, s10, v133
	v_fma_f32 v133, v205, v225, v241
	v_mul_f32_e32 v204, s10, v134
	v_fma_f32 v134, v204, v226, v242
	v_mul_f32_e32 v205, s10, v135
	v_fma_f32 v135, v205, v227, v243
	v_mul_f32_e32 v204, s10, v136
	v_fma_f32 v136, v204, v228, v244
	v_mul_f32_e32 v205, s10, v137
	v_fma_f32 v137, v205, v229, v245
	v_mul_f32_e32 v204, s10, v138
	v_fma_f32 v138, v204, v230, v246
	v_mul_f32_e32 v205, s10, v139
	v_fma_f32 v139, v205, v231, v247
	v_mul_f32_e32 v204, s10, v140
	v_fma_f32 v140, v204, v232, v248
	v_mul_f32_e32 v205, s10, v141
	v_fma_f32 v141, v205, v233, v249
	v_mul_f32_e32 v204, s10, v142
	v_fma_f32 v142, v204, v234, v250
	v_mul_f32_e32 v205, s10, v143
	v_fma_f32 v143, v205, v235, v251
	v_mul_f32_e32 v204, s10, v144
	v_fma_f32 v144, v204, v236, v252
	v_mul_f32_e32 v205, s10, v145
	v_fma_f32 v145, v205, v237, v253
	s_branch .Ln2_r10_done
.Ln2_r10_b0:
	v_mul_f32_e32 v204, s10, v130
	v_fma_f32 v130, v204, v162, v178
	v_mul_f32_e32 v205, s10, v131
	v_fma_f32 v131, v205, v163, v179
	v_mul_f32_e32 v204, s10, v132
	v_fma_f32 v132, v204, v164, v180
	v_mul_f32_e32 v205, s10, v133
	v_fma_f32 v133, v205, v165, v181
	v_mul_f32_e32 v204, s10, v134
	v_fma_f32 v134, v204, v166, v182
	v_mul_f32_e32 v205, s10, v135
	v_fma_f32 v135, v205, v167, v183
	v_mul_f32_e32 v204, s10, v136
	v_fma_f32 v136, v204, v168, v184
	v_mul_f32_e32 v205, s10, v137
	v_fma_f32 v137, v205, v169, v185
	v_mul_f32_e32 v204, s10, v138
	v_fma_f32 v138, v204, v170, v186
	v_mul_f32_e32 v205, s10, v139
	v_fma_f32 v139, v205, v171, v187
	v_mul_f32_e32 v204, s10, v140
	v_fma_f32 v140, v204, v172, v188
	v_mul_f32_e32 v205, s10, v141
	v_fma_f32 v141, v205, v173, v189
	v_mul_f32_e32 v204, s10, v142
	v_fma_f32 v142, v204, v174, v190
	v_mul_f32_e32 v205, s10, v143
	v_fma_f32 v143, v205, v175, v191
	v_mul_f32_e32 v204, s10, v144
	v_fma_f32 v144, v204, v176, v192
	v_mul_f32_e32 v205, s10, v145
	v_fma_f32 v145, v205, v177, v193
.Ln2_r10_done:
	v_cvt_pk_bf16_f32 v214, v130, v131
	v_cvt_pk_bf16_f32 v215, v132, v133
	v_cvt_pk_bf16_f32 v216, v134, v135
	v_cvt_pk_bf16_f32 v217, v136, v137
	v_cvt_pk_bf16_f32 v218, v138, v139
	v_cvt_pk_bf16_f32 v219, v140, v141
	v_cvt_pk_bf16_f32 v220, v142, v143
	v_cvt_pk_bf16_f32 v221, v144, v145
	global_store_dwordx2 v208, v[214:215], s[2:3]
	global_store_dwordx2 v208, v[216:217], s[2:3] offset:512
	global_store_dwordx2 v208, v[218:219], s[2:3] offset:1024
	global_store_dwordx2 v208, v[220:221], s[2:3] offset:1536
	s_add_u32 s2, s2, 0x60000
	s_addc_u32 s3, s3, 0
	v_mul_f32_e32 v204, s11, v146
	v_fma_f32 v146, v204, v222, v238
	v_mul_f32_e32 v205, s11, v147
	v_fma_f32 v147, v205, v223, v239
	v_mul_f32_e32 v204, s11, v148
	v_fma_f32 v148, v204, v224, v240
	v_mul_f32_e32 v205, s11, v149
	v_fma_f32 v149, v205, v225, v241
	v_mul_f32_e32 v204, s11, v150
	v_fma_f32 v150, v204, v226, v242
	v_mul_f32_e32 v205, s11, v151
	v_fma_f32 v151, v205, v227, v243
	v_mul_f32_e32 v204, s11, v152
	v_fma_f32 v152, v204, v228, v244
	v_mul_f32_e32 v205, s11, v153
	v_fma_f32 v153, v205, v229, v245
	v_mul_f32_e32 v204, s11, v154
	v_fma_f32 v154, v204, v230, v246
	v_mul_f32_e32 v205, s11, v155
	v_fma_f32 v155, v205, v231, v247
	v_mul_f32_e32 v204, s11, v156
	v_fma_f32 v156, v204, v232, v248
	v_mul_f32_e32 v205, s11, v157
	v_fma_f32 v157, v205, v233, v249
	v_mul_f32_e32 v204, s11, v158
	v_fma_f32 v158, v204, v234, v250
	v_mul_f32_e32 v205, s11, v159
	v_fma_f32 v159, v205, v235, v251
	v_mul_f32_e32 v204, s11, v160
	v_fma_f32 v160, v204, v236, v252
	v_mul_f32_e32 v205, s11, v161
	v_fma_f32 v161, v205, v237, v253
	v_cvt_pk_bf16_f32 v40, v146, v147
	v_cvt_pk_bf16_f32 v41, v148, v149
	v_cvt_pk_bf16_f32 v42, v150, v151
	v_cvt_pk_bf16_f32 v43, v152, v153
	v_cvt_pk_bf16_f32 v44, v154, v155
	v_cvt_pk_bf16_f32 v45, v156, v157
	v_cvt_pk_bf16_f32 v46, v158, v159
	v_cvt_pk_bf16_f32 v47, v160, v161
	global_store_dwordx2 v208, v[40:41], s[2:3]
	global_store_dwordx2 v208, v[42:43], s[2:3] offset:512
	global_store_dwordx2 v208, v[44:45], s[2:3] offset:1024
	global_store_dwordx2 v208, v[46:47], s[2:3] offset:1536
	s_add_u32 s2, s2, 0x60000
	s_addc_u32 s3, s3, 0
	global_load_dwordx4 v[130:133], v207, s[0:1]
	global_load_dwordx4 v[134:137], v207, s[0:1] offset:1024
	global_load_dwordx4 v[138:141], v207, s[0:1] offset:2048
	global_load_dwordx4 v[142:145], v207, s[0:1] offset:3072
	s_add_u32 s0, s0, 0xc0000
	s_addc_u32 s1, s1, 0
	global_load_dwordx4 v[146:149], v207, s[0:1]
	global_load_dwordx4 v[150:153], v207, s[0:1] offset:1024
	global_load_dwordx4 v[154:157], v207, s[0:1] offset:2048
	global_load_dwordx4 v[158:161], v207, s[0:1] offset:3072
	s_add_u32 s0, s0, 0xc0000
	s_addc_u32 s1, s1, 0
	s_waitcnt vmcnt(16)
	v_mul_f32_e32 v194, v98, v98
	v_mul_f32_e32 v195, v102, v102
	v_mul_f32_e32 v196, v106, v106
	v_mul_f32_e32 v197, v110, v110
	v_mul_f32_e32 v198, v114, v114
	v_mul_f32_e32 v199, v118, v118
	v_mul_f32_e32 v200, v122, v122
	v_mul_f32_e32 v201, v126, v126
	v_fmac_f32_e32 v194, v99, v99
	v_fmac_f32_e32 v195, v103, v103
	v_fmac_f32_e32 v196, v107, v107
	v_fmac_f32_e32 v197, v111, v111
	v_fmac_f32_e32 v198, v115, v115
	v_fmac_f32_e32 v199, v119, v119
	v_fmac_f32_e32 v200, v123, v123
	v_fmac_f32_e32 v201, v127, v127
	v_fmac_f32_e32 v194, v100, v100
	v_fmac_f32_e32 v195, v104, v104
	v_fmac_f32_e32 v196, v108, v108
	v_fmac_f32_e32 v197, v112, v112
	v_fmac_f32_e32 v198, v116, v116
	v_fmac_f32_e32 v199, v120, v120
	v_fmac_f32_e32 v200, v124, v124
	v_fmac_f32_e32 v201, v128, v128
	v_fmac_f32_e32 v194, v101, v101
	v_fmac_f32_e32 v195, v105, v105
	v_fmac_f32_e32 v196, v109, v109
	v_fmac_f32_e32 v197, v113, v113
	v_fmac_f32_e32 v198, v117, v117
	v_fmac_f32_e32 v199, v121, v121
	v_fmac_f32_e32 v200, v125, v125
	v_fmac_f32_e32 v201, v129, v129
	v_add_f32_e32 v194, v194, v195
	v_add_f32_e32 v196, v196, v197
	v_add_f32_e32 v198, v198, v199
	v_add_f32_e32 v200, v200, v201
	v_add_f32_e32 v202, v194, v196
	v_add_f32_e32 v203, v198, v200
	s_nop 0
	v_add_f32_dpp v202, v202, v202 quad_perm:[1,0,3,2] row_mask:0xf bank_mask:0xf
	v_add_f32_dpp v203, v203, v203 quad_perm:[1,0,3,2] row_mask:0xf bank_mask:0xf
	s_nop 0
	v_add_f32_dpp v202, v202, v202 quad_perm:[2,3,0,1] row_mask:0xf bank_mask:0xf
	v_add_f32_dpp v203, v203, v203 quad_perm:[2,3,0,1] row_mask:0xf bank_mask:0xf
	s_nop 0
	v_add_f32_dpp v202, v202, v202 row_half_mirror row_mask:0xf bank_mask:0xf
	v_add_f32_dpp v203, v203, v203 row_half_mirror row_mask:0xf bank_mask:0xf
	s_nop 0
	v_add_f32_dpp v202, v202, v202 row_mirror row_mask:0xf bank_mask:0xf
	v_add_f32_dpp v203, v203, v203 row_mirror row_mask:0xf bank_mask:0xf
	s_nop 0
	v_add_f32_dpp v202, v202, v202 row_bcast:15 row_mask:0xa bank_mask:0xf
	v_add_f32_dpp v203, v203, v203 row_bcast:15 row_mask:0xa bank_mask:0xf
	s_nop 0
	v_add_f32_dpp v202, v202, v202 row_bcast:31 row_mask:0xc bank_mask:0xf
	v_add_f32_dpp v203, v203, v203 row_bcast:31 row_mask:0xc bank_mask:0xf
	s_nop 0
	v_fma_f32 v202, v202, s22, v206
	v_fma_f32 v203, v203, s22, v206
	v_rsq_f32_e32 v202, v202
	v_rsq_f32_e32 v203, v203
	s_nop 0
	v_readlane_b32 s10, v202, 63
	v_readlane_b32 s11, v203, 63
	s_nop 1
	v_mul_f32_e32 v204, s10, v98
	v_fma_f32 v98, v204, v222, v238
	v_mul_f32_e32 v205, s10, v99
	v_fma_f32 v99, v205, v223, v239
	v_mul_f32_e32 v204, s10, v100
	v_fma_f32 v100, v204, v224, v240
	v_mul_f32_e32 v205, s10, v101
	v_fma_f32 v101, v205, v225, v241
	v_mul_f32_e32 v204, s10, v102
	v_fma_f32 v102, v204, v226, v242
	v_mul_f32_e32 v205, s10, v103
	v_fma_f32 v103, v205, v227, v243
	v_mul_f32_e32 v204, s10, v104
	v_fma_f32 v104, v204, v228, v244
	v_mul_f32_e32 v205, s10, v105
	v_fma_f32 v105, v205, v229, v245
	v_mul_f32_e32 v204, s10, v106
	v_fma_f32 v106, v204, v230, v246
	v_mul_f32_e32 v205, s10, v107
	v_fma_f32 v107, v205, v231, v247
	v_mul_f32_e32 v204, s10, v108
	v_fma_f32 v108, v204, v232, v248
	v_mul_f32_e32 v205, s10, v109
	v_fma_f32 v109, v205, v233, v249
	v_mul_f32_e32 v204, s10, v110
	v_fma_f32 v110, v204, v234, v250
	v_mul_f32_e32 v205, s10, v111
	v_fma_f32 v111, v205, v235, v251
	v_mul_f32_e32 v204, s10, v112
	v_fma_f32 v112, v204, v236, v252
	v_mul_f32_e32 v205, s10, v113
	v_fma_f32 v113, v205, v237, v253
	v_cvt_pk_bf16_f32 v214, v98, v99
	v_cvt_pk_bf16_f32 v215, v100, v101
	v_cvt_pk_bf16_f32 v216, v102, v103
	v_cvt_pk_bf16_f32 v217, v104, v105
	v_cvt_pk_bf16_f32 v218, v106, v107
	v_cvt_pk_bf16_f32 v219, v108, v109
	v_cvt_pk_bf16_f32 v220, v110, v111
	v_cvt_pk_bf16_f32 v221, v112, v113
	global_store_dwordx2 v208, v[214:215], s[2:3]
	global_store_dwordx2 v208, v[216:217], s[2:3] offset:512
	global_store_dwordx2 v208, v[218:219], s[2:3] offset:1024
	global_store_dwordx2 v208, v[220:221], s[2:3] offset:1536
	s_add_u32 s2, s2, 0x60000
	s_addc_u32 s3, s3, 0
	v_mul_f32_e32 v204, s11, v114
	v_fma_f32 v114, v204, v222, v238
	v_mul_f32_e32 v205, s11, v115
	v_fma_f32 v115, v205, v223, v239
	v_mul_f32_e32 v204, s11, v116
	v_fma_f32 v116, v204, v224, v240
	v_mul_f32_e32 v205, s11, v117
	v_fma_f32 v117, v205, v225, v241
	v_mul_f32_e32 v204, s11, v118
	v_fma_f32 v118, v204, v226, v242
	v_mul_f32_e32 v205, s11, v119
	v_fma_f32 v119, v205, v227, v243
	v_mul_f32_e32 v204, s11, v120
	v_fma_f32 v120, v204, v228, v244
	v_mul_f32_e32 v205, s11, v121
	v_fma_f32 v121, v205, v229, v245
	v_mul_f32_e32 v204, s11, v122
	v_fma_f32 v122, v204, v230, v246
	v_mul_f32_e32 v205, s11, v123
	v_fma_f32 v123, v205, v231, v247
	v_mul_f32_e32 v204, s11, v124
	v_fma_f32 v124, v204, v232, v248
	v_mul_f32_e32 v205, s11, v125
	v_fma_f32 v125, v205, v233, v249
	v_mul_f32_e32 v204, s11, v126
	v_fma_f32 v126, v204, v234, v250
	v_mul_f32_e32 v205, s11, v127
	v_fma_f32 v127, v205, v235, v251
	v_mul_f32_e32 v204, s11, v128
	v_fma_f32 v128, v204, v236, v252
	v_mul_f32_e32 v205, s11, v129
	v_fma_f32 v129, v205, v237, v253
	v_cvt_pk_bf16_f32 v40, v114, v115
	v_cvt_pk_bf16_f32 v41, v116, v117
	v_cvt_pk_bf16_f32 v42, v118, v119
	v_cvt_pk_bf16_f32 v43, v120, v121
	v_cvt_pk_bf16_f32 v44, v122, v123
	v_cvt_pk_bf16_f32 v45, v124, v125
	v_cvt_pk_bf16_f32 v46, v126, v127
	v_cvt_pk_bf16_f32 v47, v128, v129
	global_store_dwordx2 v208, v[40:41], s[2:3]
	global_store_dwordx2 v208, v[42:43], s[2:3] offset:512
	global_store_dwordx2 v208, v[44:45], s[2:3] offset:1024
	global_store_dwordx2 v208, v[46:47], s[2:3] offset:1536
	s_add_u32 s2, s2, 0x60000
	s_addc_u32 s3, s3, 0
	global_load_dwordx4 v[98:101], v207, s[0:1]
	global_load_dwordx4 v[102:105], v207, s[0:1] offset:1024
	global_load_dwordx4 v[106:109], v207, s[0:1] offset:2048
	global_load_dwordx4 v[110:113], v207, s[0:1] offset:3072
	s_add_u32 s0, s0, 0xc0000
	s_addc_u32 s1, s1, 0
	global_load_dwordx4 v[114:117], v207, s[0:1]
	global_load_dwordx4 v[118:121], v207, s[0:1] offset:1024
	global_load_dwordx4 v[122:125], v207, s[0:1] offset:2048
	global_load_dwordx4 v[126:129], v207, s[0:1] offset:3072
	s_add_u32 s0, s0, 0xc0000
	s_addc_u32 s1, s1, 0
	s_waitcnt vmcnt(16)
	v_mul_f32_e32 v194, v130, v130
	v_mul_f32_e32 v195, v134, v134
	v_mul_f32_e32 v196, v138, v138
	v_mul_f32_e32 v197, v142, v142
	v_mul_f32_e32 v198, v146, v146
	v_mul_f32_e32 v199, v150, v150
	v_mul_f32_e32 v200, v154, v154
	v_mul_f32_e32 v201, v158, v158
	v_fmac_f32_e32 v194, v131, v131
	v_fmac_f32_e32 v195, v135, v135
	v_fmac_f32_e32 v196, v139, v139
	v_fmac_f32_e32 v197, v143, v143
	v_fmac_f32_e32 v198, v147, v147
	v_fmac_f32_e32 v199, v151, v151
	v_fmac_f32_e32 v200, v155, v155
	v_fmac_f32_e32 v201, v159, v159
	v_fmac_f32_e32 v194, v132, v132
	v_fmac_f32_e32 v195, v136, v136
	v_fmac_f32_e32 v196, v140, v140
	v_fmac_f32_e32 v197, v144, v144
	v_fmac_f32_e32 v198, v148, v148
	v_fmac_f32_e32 v199, v152, v152
	v_fmac_f32_e32 v200, v156, v156
	v_fmac_f32_e32 v201, v160, v160
	v_fmac_f32_e32 v194, v133, v133
	v_fmac_f32_e32 v195, v137, v137
	v_fmac_f32_e32 v196, v141, v141
	v_fmac_f32_e32 v197, v145, v145
	v_fmac_f32_e32 v198, v149, v149
	v_fmac_f32_e32 v199, v153, v153
	v_fmac_f32_e32 v200, v157, v157
	v_fmac_f32_e32 v201, v161, v161
	v_add_f32_e32 v194, v194, v195
	v_add_f32_e32 v196, v196, v197
	v_add_f32_e32 v198, v198, v199
	v_add_f32_e32 v200, v200, v201
	v_add_f32_e32 v202, v194, v196
	v_add_f32_e32 v203, v198, v200
	s_nop 0
	v_add_f32_dpp v202, v202, v202 quad_perm:[1,0,3,2] row_mask:0xf bank_mask:0xf
	v_add_f32_dpp v203, v203, v203 quad_perm:[1,0,3,2] row_mask:0xf bank_mask:0xf
	s_nop 0
	v_add_f32_dpp v202, v202, v202 quad_perm:[2,3,0,1] row_mask:0xf bank_mask:0xf
	v_add_f32_dpp v203, v203, v203 quad_perm:[2,3,0,1] row_mask:0xf bank_mask:0xf
	s_nop 0
	v_add_f32_dpp v202, v202, v202 row_half_mirror row_mask:0xf bank_mask:0xf
	v_add_f32_dpp v203, v203, v203 row_half_mirror row_mask:0xf bank_mask:0xf
	s_nop 0
	v_add_f32_dpp v202, v202, v202 row_mirror row_mask:0xf bank_mask:0xf
	v_add_f32_dpp v203, v203, v203 row_mirror row_mask:0xf bank_mask:0xf
	s_nop 0
	v_add_f32_dpp v202, v202, v202 row_bcast:15 row_mask:0xa bank_mask:0xf
	v_add_f32_dpp v203, v203, v203 row_bcast:15 row_mask:0xa bank_mask:0xf
	s_nop 0
	v_add_f32_dpp v202, v202, v202 row_bcast:31 row_mask:0xc bank_mask:0xf
	v_add_f32_dpp v203, v203, v203 row_bcast:31 row_mask:0xc bank_mask:0xf
	s_nop 0
	v_fma_f32 v202, v202, s22, v206
	v_fma_f32 v203, v203, s22, v206
	v_rsq_f32_e32 v202, v202
	v_rsq_f32_e32 v203, v203
	s_nop 0
	v_readlane_b32 s10, v202, 63
	v_readlane_b32 s11, v203, 63
	s_nop 1
	v_mul_f32_e32 v204, s10, v130
	v_fma_f32 v130, v204, v222, v238
	v_mul_f32_e32 v205, s10, v131
	v_fma_f32 v131, v205, v223, v239
	v_mul_f32_e32 v204, s10, v132
	v_fma_f32 v132, v204, v224, v240
	v_mul_f32_e32 v205, s10, v133
	v_fma_f32 v133, v205, v225, v241
	v_mul_f32_e32 v204, s10, v134
	v_fma_f32 v134, v204, v226, v242
	v_mul_f32_e32 v205, s10, v135
	v_fma_f32 v135, v205, v227, v243
	v_mul_f32_e32 v204, s10, v136
	v_fma_f32 v136, v204, v228, v244
	v_mul_f32_e32 v205, s10, v137
	v_fma_f32 v137, v205, v229, v245
	v_mul_f32_e32 v204, s10, v138
	v_fma_f32 v138, v204, v230, v246
	v_mul_f32_e32 v205, s10, v139
	v_fma_f32 v139, v205, v231, v247
	v_mul_f32_e32 v204, s10, v140
	v_fma_f32 v140, v204, v232, v248
	v_mul_f32_e32 v205, s10, v141
	v_fma_f32 v141, v205, v233, v249
	v_mul_f32_e32 v204, s10, v142
	v_fma_f32 v142, v204, v234, v250
	v_mul_f32_e32 v205, s10, v143
	v_fma_f32 v143, v205, v235, v251
	v_mul_f32_e32 v204, s10, v144
	v_fma_f32 v144, v204, v236, v252
	v_mul_f32_e32 v205, s10, v145
	v_fma_f32 v145, v205, v237, v253
	v_cvt_pk_bf16_f32 v214, v130, v131
	v_cvt_pk_bf16_f32 v215, v132, v133
	v_cvt_pk_bf16_f32 v216, v134, v135
	v_cvt_pk_bf16_f32 v217, v136, v137
	v_cvt_pk_bf16_f32 v218, v138, v139
	v_cvt_pk_bf16_f32 v219, v140, v141
	v_cvt_pk_bf16_f32 v220, v142, v143
	v_cvt_pk_bf16_f32 v221, v144, v145
	global_store_dwordx2 v208, v[214:215], s[2:3]
	global_store_dwordx2 v208, v[216:217], s[2:3] offset:512
	global_store_dwordx2 v208, v[218:219], s[2:3] offset:1024
	global_store_dwordx2 v208, v[220:221], s[2:3] offset:1536
	s_add_u32 s2, s2, 0x60000
	s_addc_u32 s3, s3, 0
	v_mul_f32_e32 v204, s11, v146
	v_fma_f32 v146, v204, v222, v238
	v_mul_f32_e32 v205, s11, v147
	v_fma_f32 v147, v205, v223, v239
	v_mul_f32_e32 v204, s11, v148
	v_fma_f32 v148, v204, v224, v240
	v_mul_f32_e32 v205, s11, v149
	v_fma_f32 v149, v205, v225, v241
	v_mul_f32_e32 v204, s11, v150
	v_fma_f32 v150, v204, v226, v242
	v_mul_f32_e32 v205, s11, v151
	v_fma_f32 v151, v205, v227, v243
	v_mul_f32_e32 v204, s11, v152
	v_fma_f32 v152, v204, v228, v244
	v_mul_f32_e32 v205, s11, v153
	v_fma_f32 v153, v205, v229, v245
	v_mul_f32_e32 v204, s11, v154
	v_fma_f32 v154, v204, v230, v246
	v_mul_f32_e32 v205, s11, v155
	v_fma_f32 v155, v205, v231, v247
	v_mul_f32_e32 v204, s11, v156
	v_fma_f32 v156, v204, v232, v248
	v_mul_f32_e32 v205, s11, v157
	v_fma_f32 v157, v205, v233, v249
	v_mul_f32_e32 v204, s11, v158
	v_fma_f32 v158, v204, v234, v250
	v_mul_f32_e32 v205, s11, v159
	v_fma_f32 v159, v205, v235, v251
	v_mul_f32_e32 v204, s11, v160
	v_fma_f32 v160, v204, v236, v252
	v_mul_f32_e32 v205, s11, v161
	v_fma_f32 v161, v205, v237, v253
	v_cvt_pk_bf16_f32 v40, v146, v147
	v_cvt_pk_bf16_f32 v41, v148, v149
	v_cvt_pk_bf16_f32 v42, v150, v151
	v_cvt_pk_bf16_f32 v43, v152, v153
	v_cvt_pk_bf16_f32 v44, v154, v155
	v_cvt_pk_bf16_f32 v45, v156, v157
	v_cvt_pk_bf16_f32 v46, v158, v159
	v_cvt_pk_bf16_f32 v47, v160, v161
	global_store_dwordx2 v208, v[40:41], s[2:3]
	global_store_dwordx2 v208, v[42:43], s[2:3] offset:512
	global_store_dwordx2 v208, v[44:45], s[2:3] offset:1024
	global_store_dwordx2 v208, v[46:47], s[2:3] offset:1536
	s_add_u32 s2, s2, 0x60000
	s_addc_u32 s3, s3, 0
	global_load_dwordx4 v[130:133], v207, s[0:1]
	global_load_dwordx4 v[134:137], v207, s[0:1] offset:1024
	global_load_dwordx4 v[138:141], v207, s[0:1] offset:2048
	global_load_dwordx4 v[142:145], v207, s[0:1] offset:3072
	s_add_u32 s0, s0, 0xc0000
	s_addc_u32 s1, s1, 0
	global_load_dwordx4 v[146:149], v207, s[0:1]
	global_load_dwordx4 v[150:153], v207, s[0:1] offset:1024
	global_load_dwordx4 v[154:157], v207, s[0:1] offset:2048
	global_load_dwordx4 v[158:161], v207, s[0:1] offset:3072
	s_add_u32 s0, s0, 0xc0000
	s_addc_u32 s1, s1, 0
	s_waitcnt vmcnt(16)
	v_mul_f32_e32 v194, v98, v98
	v_mul_f32_e32 v195, v102, v102
	v_mul_f32_e32 v196, v106, v106
	v_mul_f32_e32 v197, v110, v110
	v_mul_f32_e32 v198, v114, v114
	v_mul_f32_e32 v199, v118, v118
	v_mul_f32_e32 v200, v122, v122
	v_mul_f32_e32 v201, v126, v126
	v_fmac_f32_e32 v194, v99, v99
	v_fmac_f32_e32 v195, v103, v103
	v_fmac_f32_e32 v196, v107, v107
	v_fmac_f32_e32 v197, v111, v111
	v_fmac_f32_e32 v198, v115, v115
	v_fmac_f32_e32 v199, v119, v119
	v_fmac_f32_e32 v200, v123, v123
	v_fmac_f32_e32 v201, v127, v127
	v_fmac_f32_e32 v194, v100, v100
	v_fmac_f32_e32 v195, v104, v104
	v_fmac_f32_e32 v196, v108, v108
	v_fmac_f32_e32 v197, v112, v112
	v_fmac_f32_e32 v198, v116, v116
	v_fmac_f32_e32 v199, v120, v120
	v_fmac_f32_e32 v200, v124, v124
	v_fmac_f32_e32 v201, v128, v128
	v_fmac_f32_e32 v194, v101, v101
	v_fmac_f32_e32 v195, v105, v105
	v_fmac_f32_e32 v196, v109, v109
	v_fmac_f32_e32 v197, v113, v113
	v_fmac_f32_e32 v198, v117, v117
	v_fmac_f32_e32 v199, v121, v121
	v_fmac_f32_e32 v200, v125, v125
	v_fmac_f32_e32 v201, v129, v129
	v_add_f32_e32 v194, v194, v195
	v_add_f32_e32 v196, v196, v197
	v_add_f32_e32 v198, v198, v199
	v_add_f32_e32 v200, v200, v201
	v_add_f32_e32 v202, v194, v196
	v_add_f32_e32 v203, v198, v200
	s_nop 0
	v_add_f32_dpp v202, v202, v202 quad_perm:[1,0,3,2] row_mask:0xf bank_mask:0xf
	v_add_f32_dpp v203, v203, v203 quad_perm:[1,0,3,2] row_mask:0xf bank_mask:0xf
	s_nop 0
	v_add_f32_dpp v202, v202, v202 quad_perm:[2,3,0,1] row_mask:0xf bank_mask:0xf
	v_add_f32_dpp v203, v203, v203 quad_perm:[2,3,0,1] row_mask:0xf bank_mask:0xf
	s_nop 0
	v_add_f32_dpp v202, v202, v202 row_half_mirror row_mask:0xf bank_mask:0xf
	v_add_f32_dpp v203, v203, v203 row_half_mirror row_mask:0xf bank_mask:0xf
	s_nop 0
	v_add_f32_dpp v202, v202, v202 row_mirror row_mask:0xf bank_mask:0xf
	v_add_f32_dpp v203, v203, v203 row_mirror row_mask:0xf bank_mask:0xf
	s_nop 0
	v_add_f32_dpp v202, v202, v202 row_bcast:15 row_mask:0xa bank_mask:0xf
	v_add_f32_dpp v203, v203, v203 row_bcast:15 row_mask:0xa bank_mask:0xf
	s_nop 0
	v_add_f32_dpp v202, v202, v202 row_bcast:31 row_mask:0xc bank_mask:0xf
	v_add_f32_dpp v203, v203, v203 row_bcast:31 row_mask:0xc bank_mask:0xf
	s_nop 0
	v_fma_f32 v202, v202, s22, v206
	v_fma_f32 v203, v203, s22, v206
	v_rsq_f32_e32 v202, v202
	v_rsq_f32_e32 v203, v203
	s_nop 0
	v_readlane_b32 s10, v202, 63
	v_readlane_b32 s11, v203, 63
	s_nop 1
	v_mul_f32_e32 v204, s10, v98
	v_fma_f32 v98, v204, v222, v238
	v_mul_f32_e32 v205, s10, v99
	v_fma_f32 v99, v205, v223, v239
	v_mul_f32_e32 v204, s10, v100
	v_fma_f32 v100, v204, v224, v240
	v_mul_f32_e32 v205, s10, v101
	v_fma_f32 v101, v205, v225, v241
	v_mul_f32_e32 v204, s10, v102
	v_fma_f32 v102, v204, v226, v242
	v_mul_f32_e32 v205, s10, v103
	v_fma_f32 v103, v205, v227, v243
	v_mul_f32_e32 v204, s10, v104
	v_fma_f32 v104, v204, v228, v244
	v_mul_f32_e32 v205, s10, v105
	v_fma_f32 v105, v205, v229, v245
	v_mul_f32_e32 v204, s10, v106
	v_fma_f32 v106, v204, v230, v246
	v_mul_f32_e32 v205, s10, v107
	v_fma_f32 v107, v205, v231, v247
	v_mul_f32_e32 v204, s10, v108
	v_fma_f32 v108, v204, v232, v248
	v_mul_f32_e32 v205, s10, v109
	v_fma_f32 v109, v205, v233, v249
	v_mul_f32_e32 v204, s10, v110
	v_fma_f32 v110, v204, v234, v250
	v_mul_f32_e32 v205, s10, v111
	v_fma_f32 v111, v205, v235, v251
	v_mul_f32_e32 v204, s10, v112
	v_fma_f32 v112, v204, v236, v252
	v_mul_f32_e32 v205, s10, v113
	v_fma_f32 v113, v205, v237, v253
	v_cvt_pk_bf16_f32 v214, v98, v99
	v_cvt_pk_bf16_f32 v215, v100, v101
	v_cvt_pk_bf16_f32 v216, v102, v103
	v_cvt_pk_bf16_f32 v217, v104, v105
	v_cvt_pk_bf16_f32 v218, v106, v107
	v_cvt_pk_bf16_f32 v219, v108, v109
	v_cvt_pk_bf16_f32 v220, v110, v111
	v_cvt_pk_bf16_f32 v221, v112, v113
	global_store_dwordx2 v208, v[214:215], s[2:3]
	global_store_dwordx2 v208, v[216:217], s[2:3] offset:512
	global_store_dwordx2 v208, v[218:219], s[2:3] offset:1024
	global_store_dwordx2 v208, v[220:221], s[2:3] offset:1536
	s_add_u32 s2, s2, 0x60000
	s_addc_u32 s3, s3, 0
	v_mul_f32_e32 v204, s11, v114
	v_fma_f32 v114, v204, v222, v238
	v_mul_f32_e32 v205, s11, v115
	v_fma_f32 v115, v205, v223, v239
	v_mul_f32_e32 v204, s11, v116
	v_fma_f32 v116, v204, v224, v240
	v_mul_f32_e32 v205, s11, v117
	v_fma_f32 v117, v205, v225, v241
	v_mul_f32_e32 v204, s11, v118
	v_fma_f32 v118, v204, v226, v242
	v_mul_f32_e32 v205, s11, v119
	v_fma_f32 v119, v205, v227, v243
	v_mul_f32_e32 v204, s11, v120
	v_fma_f32 v120, v204, v228, v244
	v_mul_f32_e32 v205, s11, v121
	v_fma_f32 v121, v205, v229, v245
	v_mul_f32_e32 v204, s11, v122
	v_fma_f32 v122, v204, v230, v246
	v_mul_f32_e32 v205, s11, v123
	v_fma_f32 v123, v205, v231, v247
	v_mul_f32_e32 v204, s11, v124
	v_fma_f32 v124, v204, v232, v248
	v_mul_f32_e32 v205, s11, v125
	v_fma_f32 v125, v205, v233, v249
	v_mul_f32_e32 v204, s11, v126
	v_fma_f32 v126, v204, v234, v250
	v_mul_f32_e32 v205, s11, v127
	v_fma_f32 v127, v205, v235, v251
	v_mul_f32_e32 v204, s11, v128
	v_fma_f32 v128, v204, v236, v252
	v_mul_f32_e32 v205, s11, v129
	v_fma_f32 v129, v205, v237, v253
	v_cvt_pk_bf16_f32 v40, v114, v115
	v_cvt_pk_bf16_f32 v41, v116, v117
	v_cvt_pk_bf16_f32 v42, v118, v119
	v_cvt_pk_bf16_f32 v43, v120, v121
	v_cvt_pk_bf16_f32 v44, v122, v123
	v_cvt_pk_bf16_f32 v45, v124, v125
	v_cvt_pk_bf16_f32 v46, v126, v127
	v_cvt_pk_bf16_f32 v47, v128, v129
	global_store_dwordx2 v208, v[40:41], s[2:3]
	global_store_dwordx2 v208, v[42:43], s[2:3] offset:512
	global_store_dwordx2 v208, v[44:45], s[2:3] offset:1024
	global_store_dwordx2 v208, v[46:47], s[2:3] offset:1536
	s_add_u32 s2, s2, 0x60000
	s_addc_u32 s3, s3, 0
	global_load_dwordx4 v[98:101], v207, s[0:1]
	global_load_dwordx4 v[102:105], v207, s[0:1] offset:1024
	global_load_dwordx4 v[106:109], v207, s[0:1] offset:2048
	global_load_dwordx4 v[110:113], v207, s[0:1] offset:3072
	s_add_u32 s0, s0, s23
	s_addc_u32 s1, s1, 0
	global_load_dwordx4 v[114:117], v207, s[0:1]
	global_load_dwordx4 v[118:121], v207, s[0:1] offset:1024
	global_load_dwordx4 v[122:125], v207, s[0:1] offset:2048
	global_load_dwordx4 v[126:129], v207, s[0:1] offset:3072
	s_waitcnt vmcnt(16)
	v_mul_f32_e32 v194, v130, v130
	v_mul_f32_e32 v195, v134, v134
	v_mul_f32_e32 v196, v138, v138
	v_mul_f32_e32 v197, v142, v142
	v_mul_f32_e32 v198, v146, v146
	v_mul_f32_e32 v199, v150, v150
	v_mul_f32_e32 v200, v154, v154
	v_mul_f32_e32 v201, v158, v158
	v_fmac_f32_e32 v194, v131, v131
	v_fmac_f32_e32 v195, v135, v135
	v_fmac_f32_e32 v196, v139, v139
	v_fmac_f32_e32 v197, v143, v143
	v_fmac_f32_e32 v198, v147, v147
	v_fmac_f32_e32 v199, v151, v151
	v_fmac_f32_e32 v200, v155, v155
	v_fmac_f32_e32 v201, v159, v159
	v_fmac_f32_e32 v194, v132, v132
	v_fmac_f32_e32 v195, v136, v136
	v_fmac_f32_e32 v196, v140, v140
	v_fmac_f32_e32 v197, v144, v144
	v_fmac_f32_e32 v198, v148, v148
	v_fmac_f32_e32 v199, v152, v152
	v_fmac_f32_e32 v200, v156, v156
	v_fmac_f32_e32 v201, v160, v160
	v_fmac_f32_e32 v194, v133, v133
	v_fmac_f32_e32 v195, v137, v137
	v_fmac_f32_e32 v196, v141, v141
	v_fmac_f32_e32 v197, v145, v145
	v_fmac_f32_e32 v198, v149, v149
	v_fmac_f32_e32 v199, v153, v153
	v_fmac_f32_e32 v200, v157, v157
	v_fmac_f32_e32 v201, v161, v161
	v_add_f32_e32 v194, v194, v195
	v_add_f32_e32 v196, v196, v197
	v_add_f32_e32 v198, v198, v199
	v_add_f32_e32 v200, v200, v201
	v_add_f32_e32 v202, v194, v196
	v_add_f32_e32 v203, v198, v200
	s_nop 0
	v_add_f32_dpp v202, v202, v202 quad_perm:[1,0,3,2] row_mask:0xf bank_mask:0xf
	v_add_f32_dpp v203, v203, v203 quad_perm:[1,0,3,2] row_mask:0xf bank_mask:0xf
	s_nop 0
	v_add_f32_dpp v202, v202, v202 quad_perm:[2,3,0,1] row_mask:0xf bank_mask:0xf
	v_add_f32_dpp v203, v203, v203 quad_perm:[2,3,0,1] row_mask:0xf bank_mask:0xf
	s_nop 0
	v_add_f32_dpp v202, v202, v202 row_half_mirror row_mask:0xf bank_mask:0xf
	v_add_f32_dpp v203, v203, v203 row_half_mirror row_mask:0xf bank_mask:0xf
	s_nop 0
	v_add_f32_dpp v202, v202, v202 row_mirror row_mask:0xf bank_mask:0xf
	v_add_f32_dpp v203, v203, v203 row_mirror row_mask:0xf bank_mask:0xf
	s_nop 0
	v_add_f32_dpp v202, v202, v202 row_bcast:15 row_mask:0xa bank_mask:0xf
	v_add_f32_dpp v203, v203, v203 row_bcast:15 row_mask:0xa bank_mask:0xf
	s_nop 0
	v_add_f32_dpp v202, v202, v202 row_bcast:31 row_mask:0xc bank_mask:0xf
	v_add_f32_dpp v203, v203, v203 row_bcast:31 row_mask:0xc bank_mask:0xf
	s_nop 0
	v_fma_f32 v202, v202, s22, v206
	v_fma_f32 v203, v203, s22, v206
	v_rsq_f32_e32 v202, v202
	v_rsq_f32_e32 v203, v203
	s_nop 0
	v_readlane_b32 s10, v202, 63
	v_readlane_b32 s11, v203, 63
	s_nop 1
	v_mul_f32_e32 v204, s10, v130
	v_fma_f32 v130, v204, v222, v238
	v_mul_f32_e32 v205, s10, v131
	v_fma_f32 v131, v205, v223, v239
	v_mul_f32_e32 v204, s10, v132
	v_fma_f32 v132, v204, v224, v240
	v_mul_f32_e32 v205, s10, v133
	v_fma_f32 v133, v205, v225, v241
	v_mul_f32_e32 v204, s10, v134
	v_fma_f32 v134, v204, v226, v242
	v_mul_f32_e32 v205, s10, v135
	v_fma_f32 v135, v205, v227, v243
	v_mul_f32_e32 v204, s10, v136
	v_fma_f32 v136, v204, v228, v244
	v_mul_f32_e32 v205, s10, v137
	v_fma_f32 v137, v205, v229, v245
	v_mul_f32_e32 v204, s10, v138
	v_fma_f32 v138, v204, v230, v246
	v_mul_f32_e32 v205, s10, v139
	v_fma_f32 v139, v205, v231, v247
	v_mul_f32_e32 v204, s10, v140
	v_fma_f32 v140, v204, v232, v248
	v_mul_f32_e32 v205, s10, v141
	v_fma_f32 v141, v205, v233, v249
	v_mul_f32_e32 v204, s10, v142
	v_fma_f32 v142, v204, v234, v250
	v_mul_f32_e32 v205, s10, v143
	v_fma_f32 v143, v205, v235, v251
	v_mul_f32_e32 v204, s10, v144
	v_fma_f32 v144, v204, v236, v252
	v_mul_f32_e32 v205, s10, v145
	v_fma_f32 v145, v205, v237, v253
	v_cvt_pk_bf16_f32 v214, v130, v131
	v_cvt_pk_bf16_f32 v215, v132, v133
	v_cvt_pk_bf16_f32 v216, v134, v135
	v_cvt_pk_bf16_f32 v217, v136, v137
	v_cvt_pk_bf16_f32 v218, v138, v139
	v_cvt_pk_bf16_f32 v219, v140, v141
	v_cvt_pk_bf16_f32 v220, v142, v143
	v_cvt_pk_bf16_f32 v221, v144, v145
	global_store_dwordx2 v208, v[214:215], s[2:3]
	global_store_dwordx2 v208, v[216:217], s[2:3] offset:512
	global_store_dwordx2 v208, v[218:219], s[2:3] offset:1024
	global_store_dwordx2 v208, v[220:221], s[2:3] offset:1536
	s_add_u32 s2, s2, 0x60000
	s_addc_u32 s3, s3, 0
	v_mul_f32_e32 v204, s11, v146
	v_fma_f32 v146, v204, v222, v238
	v_mul_f32_e32 v205, s11, v147
	v_fma_f32 v147, v205, v223, v239
	v_mul_f32_e32 v204, s11, v148
	v_fma_f32 v148, v204, v224, v240
	v_mul_f32_e32 v205, s11, v149
	v_fma_f32 v149, v205, v225, v241
	v_mul_f32_e32 v204, s11, v150
	v_fma_f32 v150, v204, v226, v242
	v_mul_f32_e32 v205, s11, v151
	v_fma_f32 v151, v205, v227, v243
	v_mul_f32_e32 v204, s11, v152
	v_fma_f32 v152, v204, v228, v244
	v_mul_f32_e32 v205, s11, v153
	v_fma_f32 v153, v205, v229, v245
	v_mul_f32_e32 v204, s11, v154
	v_fma_f32 v154, v204, v230, v246
	v_mul_f32_e32 v205, s11, v155
	v_fma_f32 v155, v205, v231, v247
	v_mul_f32_e32 v204, s11, v156
	v_fma_f32 v156, v204, v232, v248
	v_mul_f32_e32 v205, s11, v157
	v_fma_f32 v157, v205, v233, v249
	v_mul_f32_e32 v204, s11, v158
	v_fma_f32 v158, v204, v234, v250
	v_mul_f32_e32 v205, s11, v159
	v_fma_f32 v159, v205, v235, v251
	v_mul_f32_e32 v204, s11, v160
	v_fma_f32 v160, v204, v236, v252
	v_mul_f32_e32 v205, s11, v161
	v_fma_f32 v161, v205, v237, v253
	v_cvt_pk_bf16_f32 v40, v146, v147
	v_cvt_pk_bf16_f32 v41, v148, v149
	v_cvt_pk_bf16_f32 v42, v150, v151
	v_cvt_pk_bf16_f32 v43, v152, v153
	v_cvt_pk_bf16_f32 v44, v154, v155
	v_cvt_pk_bf16_f32 v45, v156, v157
	v_cvt_pk_bf16_f32 v46, v158, v159
	v_cvt_pk_bf16_f32 v47, v160, v161
	global_store_dwordx2 v208, v[40:41], s[2:3]
	global_store_dwordx2 v208, v[42:43], s[2:3] offset:512
	global_store_dwordx2 v208, v[44:45], s[2:3] offset:1024
	global_store_dwordx2 v208, v[46:47], s[2:3] offset:1536
	s_add_u32 s2, s2, 0x60000
	s_addc_u32 s3, s3, 0
	s_waitcnt vmcnt(8)
	v_mul_f32_e32 v194, v98, v98
	v_mul_f32_e32 v195, v102, v102
	v_mul_f32_e32 v196, v106, v106
	v_mul_f32_e32 v197, v110, v110
	v_mul_f32_e32 v198, v114, v114
	v_mul_f32_e32 v199, v118, v118
	v_mul_f32_e32 v200, v122, v122
	v_mul_f32_e32 v201, v126, v126
	v_fmac_f32_e32 v194, v99, v99
	v_fmac_f32_e32 v195, v103, v103
	v_fmac_f32_e32 v196, v107, v107
	v_fmac_f32_e32 v197, v111, v111
	v_fmac_f32_e32 v198, v115, v115
	v_fmac_f32_e32 v199, v119, v119
	v_fmac_f32_e32 v200, v123, v123
	v_fmac_f32_e32 v201, v127, v127
	v_fmac_f32_e32 v194, v100, v100
	v_fmac_f32_e32 v195, v104, v104
	v_fmac_f32_e32 v196, v108, v108
	v_fmac_f32_e32 v197, v112, v112
	v_fmac_f32_e32 v198, v116, v116
	v_fmac_f32_e32 v199, v120, v120
	v_fmac_f32_e32 v200, v124, v124
	v_fmac_f32_e32 v201, v128, v128
	v_fmac_f32_e32 v194, v101, v101
	v_fmac_f32_e32 v195, v105, v105
	v_fmac_f32_e32 v196, v109, v109
	v_fmac_f32_e32 v197, v113, v113
	v_fmac_f32_e32 v198, v117, v117
	v_fmac_f32_e32 v199, v121, v121
	v_fmac_f32_e32 v200, v125, v125
	v_fmac_f32_e32 v201, v129, v129
	v_add_f32_e32 v194, v194, v195
	v_add_f32_e32 v196, v196, v197
	v_add_f32_e32 v198, v198, v199
	v_add_f32_e32 v200, v200, v201
	v_add_f32_e32 v202, v194, v196
	v_add_f32_e32 v203, v198, v200
	s_nop 0
	v_add_f32_dpp v202, v202, v202 quad_perm:[1,0,3,2] row_mask:0xf bank_mask:0xf
	v_add_f32_dpp v203, v203, v203 quad_perm:[1,0,3,2] row_mask:0xf bank_mask:0xf
	s_nop 0
	v_add_f32_dpp v202, v202, v202 quad_perm:[2,3,0,1] row_mask:0xf bank_mask:0xf
	v_add_f32_dpp v203, v203, v203 quad_perm:[2,3,0,1] row_mask:0xf bank_mask:0xf
	s_nop 0
	v_add_f32_dpp v202, v202, v202 row_half_mirror row_mask:0xf bank_mask:0xf
	v_add_f32_dpp v203, v203, v203 row_half_mirror row_mask:0xf bank_mask:0xf
	s_nop 0
	v_add_f32_dpp v202, v202, v202 row_mirror row_mask:0xf bank_mask:0xf
	v_add_f32_dpp v203, v203, v203 row_mirror row_mask:0xf bank_mask:0xf
	s_nop 0
	v_add_f32_dpp v202, v202, v202 row_bcast:15 row_mask:0xa bank_mask:0xf
	v_add_f32_dpp v203, v203, v203 row_bcast:15 row_mask:0xa bank_mask:0xf
	s_nop 0
	v_add_f32_dpp v202, v202, v202 row_bcast:31 row_mask:0xc bank_mask:0xf
	v_add_f32_dpp v203, v203, v203 row_bcast:31 row_mask:0xc bank_mask:0xf
	s_nop 0
	v_fma_f32 v202, v202, s22, v206
	v_fma_f32 v203, v203, s22, v206
	v_rsq_f32_e32 v202, v202
	v_rsq_f32_e32 v203, v203
	s_nop 0
	v_readlane_b32 s10, v202, 63
	v_readlane_b32 s11, v203, 63
	s_nop 1
	v_mul_f32_e32 v204, s10, v98
	v_fma_f32 v98, v204, v222, v238
	v_mul_f32_e32 v205, s10, v99
	v_fma_f32 v99, v205, v223, v239
	v_mul_f32_e32 v204, s10, v100
	v_fma_f32 v100, v204, v224, v240
	v_mul_f32_e32 v205, s10, v101
	v_fma_f32 v101, v205, v225, v241
	v_mul_f32_e32 v204, s10, v102
	v_fma_f32 v102, v204, v226, v242
	v_mul_f32_e32 v205, s10, v103
	v_fma_f32 v103, v205, v227, v243
	v_mul_f32_e32 v204, s10, v104
	v_fma_f32 v104, v204, v228, v244
	v_mul_f32_e32 v205, s10, v105
	v_fma_f32 v105, v205, v229, v245
	v_mul_f32_e32 v204, s10, v106
	v_fma_f32 v106, v204, v230, v246
	v_mul_f32_e32 v205, s10, v107
	v_fma_f32 v107, v205, v231, v247
	v_mul_f32_e32 v204, s10, v108
	v_fma_f32 v108, v204, v232, v248
	v_mul_f32_e32 v205, s10, v109
	v_fma_f32 v109, v205, v233, v249
	v_mul_f32_e32 v204, s10, v110
	v_fma_f32 v110, v204, v234, v250
	v_mul_f32_e32 v205, s10, v111
	v_fma_f32 v111, v205, v235, v251
	v_mul_f32_e32 v204, s10, v112
	v_fma_f32 v112, v204, v236, v252
	v_mul_f32_e32 v205, s10, v113
	v_fma_f32 v113, v205, v237, v253
	v_cvt_pk_bf16_f32 v214, v98, v99
	v_cvt_pk_bf16_f32 v215, v100, v101
	v_cvt_pk_bf16_f32 v216, v102, v103
	v_cvt_pk_bf16_f32 v217, v104, v105
	v_cvt_pk_bf16_f32 v218, v106, v107
	v_cvt_pk_bf16_f32 v219, v108, v109
	v_cvt_pk_bf16_f32 v220, v110, v111
	v_cvt_pk_bf16_f32 v221, v112, v113
	global_store_dwordx2 v208, v[214:215], s[2:3]
	global_store_dwordx2 v208, v[216:217], s[2:3] offset:512
	global_store_dwordx2 v208, v[218:219], s[2:3] offset:1024
	global_store_dwordx2 v208, v[220:221], s[2:3] offset:1536
	s_add_u32 s2, s2, s28
	s_addc_u32 s3, s3, 0
	v_mul_f32_e32 v204, s11, v114
	v_fma_f32 v114, v204, v222, v238
	v_mul_f32_e32 v205, s11, v115
	v_fma_f32 v115, v205, v223, v239
	v_mul_f32_e32 v204, s11, v116
	v_fma_f32 v116, v204, v224, v240
	v_mul_f32_e32 v205, s11, v117
	v_fma_f32 v117, v205, v225, v241
	v_mul_f32_e32 v204, s11, v118
	v_fma_f32 v118, v204, v226, v242
	v_mul_f32_e32 v205, s11, v119
	v_fma_f32 v119, v205, v227, v243
	v_mul_f32_e32 v204, s11, v120
	v_fma_f32 v120, v204, v228, v244
	v_mul_f32_e32 v205, s11, v121
	v_fma_f32 v121, v205, v229, v245
	v_mul_f32_e32 v204, s11, v122
	v_fma_f32 v122, v204, v230, v246
	v_mul_f32_e32 v205, s11, v123
	v_fma_f32 v123, v205, v231, v247
	v_mul_f32_e32 v204, s11, v124
	v_fma_f32 v124, v204, v232, v248
	v_mul_f32_e32 v205, s11, v125
	v_fma_f32 v125, v205, v233, v249
	v_mul_f32_e32 v204, s11, v126
	v_fma_f32 v126, v204, v234, v250
	v_mul_f32_e32 v205, s11, v127
	v_fma_f32 v127, v205, v235, v251
	v_mul_f32_e32 v204, s11, v128
	v_fma_f32 v128, v204, v236, v252
	v_mul_f32_e32 v205, s11, v129
	v_fma_f32 v129, v205, v237, v253
	v_cvt_pk_bf16_f32 v40, v114, v115
	v_cvt_pk_bf16_f32 v41, v116, v117
	v_cvt_pk_bf16_f32 v42, v118, v119
	v_cvt_pk_bf16_f32 v43, v120, v121
	v_cvt_pk_bf16_f32 v44, v122, v123
	v_cvt_pk_bf16_f32 v45, v124, v125
	v_cvt_pk_bf16_f32 v46, v126, v127
	v_cvt_pk_bf16_f32 v47, v128, v129
	global_store_dwordx2 v208, v[40:41], s[2:3]
	global_store_dwordx2 v208, v[42:43], s[2:3] offset:512
	global_store_dwordx2 v208, v[44:45], s[2:3] offset:1024
	global_store_dwordx2 v208, v[46:47], s[2:3] offset:1536
	s_branch .LBB0_443
